# as v27 plus: the satisfied lgkmcnt waits and the back-to-back priority flip inside the MFMA blocks removed (compute segments are pure MFMA streams)
# speedup vs baseline: 1.0173x; 1.0046x over previous
.LBB0_382:
	s_add_i32 s39, s33, 1
	s_mov_b32 s47, s37
	s_add_i32 s37, s39, s35
	s_mul_i32 s37, s37, s23
	s_add_i32 s37, s37, s22
	s_mov_b32 s43, s38
	s_add_i32 s38, s37, 0xffffff28
	s_cmpk_lt_i32 s38, 0x48
	s_cselect_b64 s[76:77], -1, 0
	s_cmpk_gt_i32 s38, 0x47
	s_cselect_b64 s[72:73], -1, 0
	s_cmp_lt_i32 s38, 36
	s_cselect_b32 s41, 0, 0xffffffdc
	s_cselect_b32 s44, 0, 4
	s_add_i32 s38, s41, s38
	s_and_b32 s45, s37, 3
	s_ashr_i32 s37, s38, 2
	s_or_b32 s38, s45, s44
	s_or_b32 s38, s38, s28
	s_and_b64 s[44:45], s[76:77], exec
	s_cselect_b32 s80, s38, s43
	s_cselect_b32 s44, s37, s47
	s_ashr_i32 s81, s80, 31
	s_lshl_b64 s[50:51], s[80:81], 19
	s_add_u32 s74, s9, s50
	s_addc_u32 s75, s18, s51
	s_ashr_i32 s45, s44, 31
	s_lshl_b64 s[44:45], s[44:45], 19
	s_add_u32 s78, s14, s44
	s_addc_u32 s79, s15, s45
	s_add_u32 s84, s66, 0x100
	s_addc_u32 s85, s67, 0
	v_add_u32_e32 v142, 0x10000, v140
	v_add_u32_e32 v143, 0x14000, v140
	s_add_u32 s82, s66, 0x180
	ds_read_b128 v[4:7], v142
	ds_read_b128 v[8:11], v142 offset:1024
	ds_read_b128 v[12:15], v142 offset:2048
	ds_read_b128 v[16:19], v142 offset:3072
	ds_read_b128 v[20:23], v143
	ds_read_b128 v[24:27], v143 offset:1024
	ds_read_b128 v[28:31], v143 offset:2048
	ds_read_b128 v[32:35], v143 offset:3072
	s_addc_u32 s83, s67, 0
	s_and_b64 s[44:45], s[76:77], exec
	s_cselect_b32 s43, s75, s67
	s_cselect_b32 s44, s74, s66
	s_add_u32 s50, s12, 0x100
	s_addc_u32 s51, s13, 0
	s_and_b64 s[52:53], s[76:77], exec
	s_mov_b32 s41, 2
	s_cselect_b32 s45, s79, s13
	s_cselect_b32 s47, s78, s12
	ds_read_b128 v[36:39], v141
	ds_read_b128 v[40:43], v141 offset:1024
	ds_read_b128 v[44:47], v141 offset:2048
	ds_read_b128 v[48:51], v141 offset:3072
	ds_read_b128 v[52:55], v141 offset:4096
	ds_read_b128 v[56:59], v141 offset:5120
	ds_read_b128 v[60:63], v141 offset:6144
	ds_read_b128 v[64:67], v141 offset:7168
	s_add_u32 s52, s66, 0x40080
	s_addc_u32 s53, s67, 0
	s_add_i32 m0, s16, 0xc000
	s_nop 0
	global_load_lds_dwordx4 v136, s[52:53]
	s_nop 0
	s_add_i32 m0, s16, 0xe000
	s_nop 0
	global_load_lds_dwordx4 v137, s[52:53]
	s_waitcnt vmcnt(8)
	s_waitcnt lgkmcnt(0)
	s_setprio 1
	s_barrier
	v_mfma_f32_16x16x32_bf16 v[68:71], v[4:7], v[36:39], 0
	v_mfma_f32_16x16x32_bf16 v[72:75], v[12:15], v[36:39], 0
	v_mfma_f32_16x16x32_bf16 v[76:79], v[4:7], v[44:47], 0
	v_mfma_f32_16x16x32_bf16 v[80:83], v[12:15], v[44:47], 0
	v_mfma_f32_16x16x32_bf16 v[84:87], v[4:7], v[52:55], 0
	v_mfma_f32_16x16x32_bf16 v[88:91], v[12:15], v[52:55], 0
	v_mfma_f32_16x16x32_bf16 v[92:95], v[4:7], v[60:63], 0
	v_mfma_f32_16x16x32_bf16 v[96:99], v[12:15], v[60:63], 0
	v_mfma_f32_16x16x32_bf16 v[68:71], v[8:11], v[40:43], v[68:71]
	v_mfma_f32_16x16x32_bf16 v[72:75], v[16:19], v[40:43], v[72:75]
	v_mfma_f32_16x16x32_bf16 v[76:79], v[8:11], v[48:51], v[76:79]
	v_mfma_f32_16x16x32_bf16 v[80:83], v[16:19], v[48:51], v[80:83]
	v_mfma_f32_16x16x32_bf16 v[84:87], v[8:11], v[56:59], v[84:87]
	v_mfma_f32_16x16x32_bf16 v[88:91], v[16:19], v[56:59], v[88:91]
	v_mfma_f32_16x16x32_bf16 v[92:95], v[8:11], v[64:67], v[92:95]
	v_mfma_f32_16x16x32_bf16 v[100:103], v[16:19], v[64:67], v[96:99]
	v_mfma_f32_16x16x32_bf16 v[96:99], v[20:23], v[36:39], 0
	v_mfma_f32_16x16x32_bf16 v[36:39], v[28:31], v[36:39], 0
	v_mfma_f32_16x16x32_bf16 v[108:111], v[24:27], v[40:43], v[96:99]
	v_mfma_f32_16x16x32_bf16 v[36:39], v[32:35], v[40:43], v[36:39]
	v_mfma_f32_16x16x32_bf16 v[40:43], v[20:23], v[44:47], 0
	v_mfma_f32_16x16x32_bf16 v[44:47], v[28:31], v[44:47], 0
	v_mfma_f32_16x16x32_bf16 v[40:43], v[24:27], v[48:51], v[40:43]
	v_mfma_f32_16x16x32_bf16 v[44:47], v[32:35], v[48:51], v[44:47]
	v_mfma_f32_16x16x32_bf16 v[48:51], v[20:23], v[52:55], 0
	v_mfma_f32_16x16x32_bf16 v[52:55], v[28:31], v[52:55], 0
	v_mfma_f32_16x16x32_bf16 v[48:51], v[24:27], v[56:59], v[48:51]
	v_mfma_f32_16x16x32_bf16 v[52:55], v[32:35], v[56:59], v[52:55]
	v_mfma_f32_16x16x32_bf16 v[56:59], v[20:23], v[60:63], 0
	v_mfma_f32_16x16x32_bf16 v[146:149], v[24:27], v[64:67], v[56:59]
	v_mfma_f32_16x16x32_bf16 v[56:59], v[28:31], v[60:63], 0
	v_mfma_f32_16x16x32_bf16 v[150:153], v[32:35], v[64:67], v[56:59]
	s_barrier
	s_setprio 0
	s_nop 4
	ds_read_b128 v[56:59], v141 offset:16384
	ds_read_b128 v[60:63], v141 offset:17408
	ds_read_b128 v[64:67], v141 offset:18432
	ds_read_b128 v[96:99], v141 offset:19456
	ds_read_b128 v[104:107], v141 offset:20480
	ds_read_b128 v[112:115], v141 offset:21504
	ds_read_b128 v[116:119], v141 offset:22528
	ds_read_b128 v[120:123], v141 offset:23552
	s_add_i32 m0, s16, 0x10000
	s_nop 0
	global_load_lds_dwordx4 v1, s[50:51]
	s_nop 0
	s_add_i32 m0, s16, 0x12000
	s_nop 0
	global_load_lds_dwordx4 v134, s[50:51]
	s_add_u32 s50, s12, 0x40100
	s_addc_u32 s51, s13, 0
	s_add_i32 m0, s16, 0x14000
	s_nop 0
	global_load_lds_dwordx4 v1, s[50:51]
	s_nop 0
	s_add_i32 m0, s16, 0x16000
	s_nop 0
	global_load_lds_dwordx4 v134, s[50:51]
	s_nop 0
	s_add_i32 m0, s16, 0
	s_nop 0
	global_load_lds_dwordx4 v136, s[84:85]
	s_nop 0
	s_add_i32 m0, s16, 0x2000
	s_nop 0
	global_load_lds_dwordx4 v137, s[84:85]
	s_waitcnt vmcnt(8)
	s_waitcnt lgkmcnt(0)
	s_setprio 1
	s_barrier
	v_mfma_f32_16x16x32_bf16 v[124:127], v[4:7], v[56:59], 0
	v_mfma_f32_16x16x32_bf16 v[154:157], v[8:11], v[60:63], v[124:127]
	v_mfma_f32_16x16x32_bf16 v[124:127], v[12:15], v[56:59], 0
	v_mfma_f32_16x16x32_bf16 v[158:161], v[16:19], v[60:63], v[124:127]
	v_mfma_f32_16x16x32_bf16 v[124:127], v[4:7], v[64:67], 0
	v_mfma_f32_16x16x32_bf16 v[162:165], v[8:11], v[96:99], v[124:127]
	v_mfma_f32_16x16x32_bf16 v[124:127], v[12:15], v[64:67], 0
	v_mfma_f32_16x16x32_bf16 v[166:169], v[16:19], v[96:99], v[124:127]
	v_mfma_f32_16x16x32_bf16 v[124:127], v[4:7], v[104:107], 0
	v_mfma_f32_16x16x32_bf16 v[4:7], v[4:7], v[116:119], 0
	v_mfma_f32_16x16x32_bf16 v[172:175], v[8:11], v[112:115], v[124:127]
	v_mfma_f32_16x16x32_bf16 v[4:7], v[8:11], v[120:123], v[4:7]
	v_mfma_f32_16x16x32_bf16 v[8:11], v[12:15], v[116:119], 0
	v_mfma_f32_16x16x32_bf16 v[124:127], v[12:15], v[104:107], 0
	v_mfma_f32_16x16x32_bf16 v[8:11], v[16:19], v[120:123], v[8:11]
	v_mfma_f32_16x16x32_bf16 v[176:179], v[16:19], v[112:115], v[124:127]
	v_mfma_f32_16x16x32_bf16 v[16:19], v[28:31], v[56:59], 0
	v_mfma_f32_16x16x32_bf16 v[180:183], v[32:35], v[60:63], v[16:19]
	v_mfma_f32_16x16x32_bf16 v[16:19], v[20:23], v[64:67], 0
	v_mfma_f32_16x16x32_bf16 v[184:187], v[24:27], v[96:99], v[16:19]
	v_mfma_f32_16x16x32_bf16 v[16:19], v[28:31], v[64:67], 0
	v_mfma_f32_16x16x32_bf16 v[188:191], v[32:35], v[96:99], v[16:19]
	v_mfma_f32_16x16x32_bf16 v[16:19], v[20:23], v[104:107], 0
	v_mfma_f32_16x16x32_bf16 v[196:199], v[24:27], v[112:115], v[16:19]
	v_mfma_f32_16x16x32_bf16 v[16:19], v[28:31], v[104:107], 0
	v_mfma_f32_16x16x32_bf16 v[12:15], v[20:23], v[56:59], 0
	v_mfma_f32_16x16x32_bf16 v[200:203], v[32:35], v[112:115], v[16:19]
	v_mfma_f32_16x16x32_bf16 v[16:19], v[20:23], v[116:119], 0
	v_mfma_f32_16x16x32_bf16 v[12:15], v[24:27], v[60:63], v[12:15]
	v_mfma_f32_16x16x32_bf16 v[204:207], v[24:27], v[120:123], v[16:19]
	v_mfma_f32_16x16x32_bf16 v[16:19], v[28:31], v[116:119], 0
	v_mfma_f32_16x16x32_bf16 v[208:211], v[32:35], v[120:123], v[16:19]
	s_barrier
	s_setprio 0
	v_add_u32_e32 v144, 0x18000, v140
	v_add_u32_e32 v145, 0x1c000, v140
	s_nop 2
	ds_read_b128 v[16:19], v144
	ds_read_b128 v[20:23], v144 offset:1024
	ds_read_b128 v[28:31], v144 offset:2048
	ds_read_b128 v[212:215], v144 offset:3072
	ds_read_b128 v[216:219], v145
	ds_read_b128 v[220:223], v145 offset:1024
	ds_read_b128 v[224:227], v145 offset:2048
	ds_read_b128 v[228:231], v145 offset:3072
	ds_read_b128 v[24:27], v141 offset:32768
	ds_read_b128 v[32:35], v141 offset:33792
	ds_read_b128 v[60:63], v141 offset:34816
	ds_read_b128 v[232:235], v141 offset:35840
	ds_read_b128 v[236:239], v141 offset:36864
	ds_read_b128 v[240:243], v141 offset:37888
	ds_read_b128 v[244:247], v141 offset:38912
	ds_read_b128 v[248:251], v141 offset:39936
	s_add_u32 s50, s66, 0x40100
	s_addc_u32 s51, s67, 0
	s_add_i32 m0, s16, 0x4000
	s_nop 0
	global_load_lds_dwordx4 v136, s[50:51]
	s_nop 0
	s_add_i32 m0, s16, 0x6000
	s_nop 0
	global_load_lds_dwordx4 v137, s[50:51]
	s_waitcnt vmcnt(8)
	s_waitcnt lgkmcnt(0)
	s_setprio 1
	s_barrier
	v_mfma_f32_16x16x32_bf16 v[56:59], v[16:19], v[24:27], v[68:71]
	v_mfma_f32_16x16x32_bf16 v[128:131], v[20:23], v[32:35], v[56:59]
	v_mfma_f32_16x16x32_bf16 v[56:59], v[28:31], v[24:27], v[72:75]
	v_mfma_f32_16x16x32_bf16 v[120:123], v[212:215], v[32:35], v[56:59]
	v_mfma_f32_16x16x32_bf16 v[56:59], v[16:19], v[60:63], v[76:79]
	v_mfma_f32_16x16x32_bf16 v[112:115], v[20:23], v[232:235], v[56:59]
	v_mfma_f32_16x16x32_bf16 v[56:59], v[28:31], v[60:63], v[80:83]
	v_mfma_f32_16x16x32_bf16 v[104:107], v[212:215], v[232:235], v[56:59]
	v_mfma_f32_16x16x32_bf16 v[56:59], v[16:19], v[236:239], v[84:87]
	v_mfma_f32_16x16x32_bf16 v[96:99], v[20:23], v[240:243], v[56:59]
	v_mfma_f32_16x16x32_bf16 v[56:59], v[28:31], v[236:239], v[88:91]
	v_mfma_f32_16x16x32_bf16 v[88:91], v[212:215], v[240:243], v[56:59]
	v_mfma_f32_16x16x32_bf16 v[56:59], v[16:19], v[244:247], v[92:95]
	v_mfma_f32_16x16x32_bf16 v[64:67], v[20:23], v[248:251], v[56:59]
	v_mfma_f32_16x16x32_bf16 v[56:59], v[28:31], v[244:247], v[100:103]
	v_mfma_f32_16x16x32_bf16 v[56:59], v[212:215], v[248:251], v[56:59]
	v_mfma_f32_16x16x32_bf16 v[68:71], v[216:219], v[24:27], v[108:111]
	v_mfma_f32_16x16x32_bf16 v[24:27], v[224:227], v[24:27], v[36:39]
	v_mfma_f32_16x16x32_bf16 v[116:119], v[228:231], v[32:35], v[24:27]
	v_mfma_f32_16x16x32_bf16 v[24:27], v[216:219], v[60:63], v[40:43]
	v_mfma_f32_16x16x32_bf16 v[108:111], v[220:223], v[232:235], v[24:27]
	v_mfma_f32_16x16x32_bf16 v[24:27], v[224:227], v[60:63], v[44:47]
	v_mfma_f32_16x16x32_bf16 v[100:103], v[228:231], v[232:235], v[24:27]
	v_mfma_f32_16x16x32_bf16 v[24:27], v[216:219], v[236:239], v[48:51]
	v_mfma_f32_16x16x32_bf16 v[92:95], v[220:223], v[240:243], v[24:27]
	v_mfma_f32_16x16x32_bf16 v[24:27], v[224:227], v[236:239], v[52:55]
	v_mfma_f32_16x16x32_bf16 v[84:87], v[228:231], v[240:243], v[24:27]
	v_mfma_f32_16x16x32_bf16 v[24:27], v[216:219], v[244:247], v[146:149]
	v_mfma_f32_16x16x32_bf16 v[60:63], v[220:223], v[248:251], v[24:27]
	v_mfma_f32_16x16x32_bf16 v[24:27], v[224:227], v[244:247], v[150:153]
	v_mfma_f32_16x16x32_bf16 v[124:127], v[220:223], v[32:35], v[68:71]
	v_mfma_f32_16x16x32_bf16 v[52:55], v[228:231], v[248:251], v[24:27]
	s_barrier
	s_setprio 0
	s_add_u32 s50, s12, 0x180
	ds_read_b128 v[36:39], v141 offset:49152
	ds_read_b128 v[44:47], v141 offset:50176
	ds_read_b128 v[146:149], v141 offset:51200
	ds_read_b128 v[150:153], v141 offset:52224
	ds_read_b128 v[232:235], v141 offset:53248
	ds_read_b128 v[236:239], v141 offset:54272
	ds_read_b128 v[240:243], v141 offset:55296
	ds_read_b128 v[244:247], v141 offset:56320
	s_addc_u32 s51, s13, 0
	s_add_i32 m0, s16, 0x18000
	s_nop 0
	global_load_lds_dwordx4 v1, s[50:51]
	s_nop 0
	s_add_i32 m0, s16, 0x1a000
	s_nop 0
	global_load_lds_dwordx4 v134, s[50:51]
	s_add_u32 s50, s12, 0x40180
	s_addc_u32 s51, s13, 0
	s_add_i32 m0, s16, 0x1c000
	s_nop 0
	global_load_lds_dwordx4 v1, s[50:51]
	s_nop 0
	s_add_i32 m0, s16, 0x1e000
	s_nop 0
	global_load_lds_dwordx4 v134, s[50:51]
	s_nop 0
	s_add_i32 m0, s16, 0x8000
	s_nop 0
	global_load_lds_dwordx4 v136, s[82:83]
	s_nop 0
	s_add_i32 m0, s16, 0xa000
	s_nop 0
	global_load_lds_dwordx4 v137, s[82:83]
	s_waitcnt vmcnt(8)
	s_waitcnt lgkmcnt(0)
	s_setprio 1
	s_barrier
	v_mfma_f32_16x16x32_bf16 v[24:27], v[16:19], v[36:39], v[154:157]
	v_mfma_f32_16x16x32_bf16 v[80:83], v[20:23], v[44:47], v[24:27]
	v_mfma_f32_16x16x32_bf16 v[24:27], v[28:31], v[36:39], v[158:161]
	v_mfma_f32_16x16x32_bf16 v[72:75], v[212:215], v[44:47], v[24:27]
	v_mfma_f32_16x16x32_bf16 v[24:27], v[16:19], v[146:149], v[162:165]
	v_mfma_f32_16x16x32_bf16 v[48:51], v[20:23], v[150:153], v[24:27]
	v_mfma_f32_16x16x32_bf16 v[24:27], v[28:31], v[146:149], v[166:169]
	v_mfma_f32_16x16x32_bf16 v[40:43], v[212:215], v[150:153], v[24:27]
	v_mfma_f32_16x16x32_bf16 v[24:27], v[16:19], v[232:235], v[172:175]
	v_mfma_f32_16x16x32_bf16 v[4:7], v[16:19], v[240:243], v[4:7]
	v_mfma_f32_16x16x32_bf16 v[32:35], v[20:23], v[236:239], v[24:27]
	v_mfma_f32_16x16x32_bf16 v[24:27], v[28:31], v[232:235], v[176:179]
	v_mfma_f32_16x16x32_bf16 v[16:19], v[20:23], v[244:247], v[4:7]
	v_mfma_f32_16x16x32_bf16 v[4:7], v[28:31], v[240:243], v[8:11]
	v_mfma_f32_16x16x32_bf16 v[24:27], v[212:215], v[236:239], v[24:27]
	v_mfma_f32_16x16x32_bf16 v[8:11], v[212:215], v[244:247], v[4:7]
	v_mfma_f32_16x16x32_bf16 v[4:7], v[216:219], v[36:39], v[12:15]
	v_mfma_f32_16x16x32_bf16 v[76:79], v[220:223], v[44:47], v[4:7]
	v_mfma_f32_16x16x32_bf16 v[4:7], v[224:227], v[36:39], v[180:183]
	v_mfma_f32_16x16x32_bf16 v[68:71], v[228:231], v[44:47], v[4:7]
	v_mfma_f32_16x16x32_bf16 v[4:7], v[216:219], v[146:149], v[184:187]
	v_mfma_f32_16x16x32_bf16 v[44:47], v[220:223], v[150:153], v[4:7]
	v_mfma_f32_16x16x32_bf16 v[4:7], v[224:227], v[146:149], v[188:191]
	v_mfma_f32_16x16x32_bf16 v[36:39], v[228:231], v[150:153], v[4:7]
	v_mfma_f32_16x16x32_bf16 v[4:7], v[216:219], v[232:235], v[196:199]
	v_mfma_f32_16x16x32_bf16 v[28:31], v[220:223], v[236:239], v[4:7]
	v_mfma_f32_16x16x32_bf16 v[4:7], v[224:227], v[232:235], v[200:203]
	v_mfma_f32_16x16x32_bf16 v[20:23], v[228:231], v[236:239], v[4:7]
	v_mfma_f32_16x16x32_bf16 v[4:7], v[216:219], v[240:243], v[204:207]
	v_mfma_f32_16x16x32_bf16 v[12:15], v[220:223], v[244:247], v[4:7]
	v_mfma_f32_16x16x32_bf16 v[4:7], v[224:227], v[240:243], v[208:211]
	v_mfma_f32_16x16x32_bf16 v[4:7], v[228:231], v[244:247], v[4:7]
	s_barrier
	s_setprio 0
	s_lshl_b32 s50, s80, 6
	s_addk_i32 s50, 0x4000
	s_lshl_b64 s[52:53], s[80:81], 14
	s_add_u32 s82, s6, s52
	s_addc_u32 s83, s7, s53
	s_lshl_b32 s51, s80, 8
	s_and_b32 s51, s51, 0x400
	s_add_i32 s51, s51, 0
	s_add_i32 s51, s51, 0x24400

.LBB0_402:
	s_lshl_b32 s54, s41, 7
	s_add_u32 s55, s66, s54
	s_addc_u32 s56, s67, 0
	s_add_u32 s58, s55, 0x100
	ds_read_b128 v[146:149], v142
	ds_read_b128 v[150:153], v142 offset:1024
	ds_read_b128 v[154:157], v142 offset:2048
	ds_read_b128 v[158:161], v142 offset:3072
	ds_read_b128 v[162:165], v143
	ds_read_b128 v[166:169], v143 offset:1024
	ds_read_b128 v[172:175], v143 offset:2048
	ds_read_b128 v[176:179], v143 offset:3072
	s_addc_u32 s59, s56, 0
	s_and_b64 s[52:53], s[84:85], exec
	s_cselect_b32 s91, s43, s59
	s_cselect_b32 s90, s44, s58
	s_add_u32 s52, s12, s54
	s_addc_u32 s53, s13, 0
	s_add_u32 s54, s52, 0x100
	s_addc_u32 s58, s53, 0
	s_and_b64 s[52:53], s[84:85], exec
	s_cselect_b32 s85, s45, s58
	s_cselect_b32 s84, s47, s54
	s_add_u32 s86, s90, 0x80
	s_addc_u32 s87, s91, 0
	s_waitcnt lgkmcnt(0)
	s_add_u32 s88, s84, 0x80
	s_addc_u32 s89, s85, 0
	ds_read_b128 v[180:183], v141
	ds_read_b128 v[184:187], v141 offset:1024
	ds_read_b128 v[188:191], v141 offset:2048
	ds_read_b128 v[196:199], v141 offset:3072
	ds_read_b128 v[200:203], v141 offset:4096
	ds_read_b128 v[204:207], v141 offset:5120
	ds_read_b128 v[208:211], v141 offset:6144
	ds_read_b128 v[212:215], v141 offset:7168
	s_add_u32 s52, s55, 0x40080
	s_addc_u32 s53, s56, 0
	s_add_i32 m0, s16, 0xc000
	s_nop 0
	global_load_lds_dwordx4 v136, s[52:53]
	s_nop 0
	s_add_i32 m0, s16, 0xe000
	s_nop 0
	global_load_lds_dwordx4 v137, s[52:53]
	s_waitcnt vmcnt(8)
	s_waitcnt lgkmcnt(0)
	s_setprio 1
	s_barrier
	v_mfma_f32_16x16x32_bf16 v[128:131], v[146:149], v[180:183], v[128:131]
	v_mfma_f32_16x16x32_bf16 v[120:123], v[154:157], v[180:183], v[120:123]
	v_mfma_f32_16x16x32_bf16 v[112:115], v[146:149], v[188:191], v[112:115]
	v_mfma_f32_16x16x32_bf16 v[104:107], v[154:157], v[188:191], v[104:107]
	v_mfma_f32_16x16x32_bf16 v[96:99], v[146:149], v[200:203], v[96:99]
	v_mfma_f32_16x16x32_bf16 v[88:91], v[154:157], v[200:203], v[88:91]
	v_mfma_f32_16x16x32_bf16 v[64:67], v[146:149], v[208:211], v[64:67]
	v_mfma_f32_16x16x32_bf16 v[56:59], v[154:157], v[208:211], v[56:59]
	v_mfma_f32_16x16x32_bf16 v[128:131], v[150:153], v[184:187], v[128:131]
	v_mfma_f32_16x16x32_bf16 v[120:123], v[158:161], v[184:187], v[120:123]
	v_mfma_f32_16x16x32_bf16 v[112:115], v[150:153], v[196:199], v[112:115]
	v_mfma_f32_16x16x32_bf16 v[104:107], v[158:161], v[196:199], v[104:107]
	v_mfma_f32_16x16x32_bf16 v[96:99], v[150:153], v[204:207], v[96:99]
	v_mfma_f32_16x16x32_bf16 v[88:91], v[158:161], v[204:207], v[88:91]
	v_mfma_f32_16x16x32_bf16 v[64:67], v[150:153], v[212:215], v[64:67]
	v_mfma_f32_16x16x32_bf16 v[56:59], v[158:161], v[212:215], v[56:59]
	v_mfma_f32_16x16x32_bf16 v[124:127], v[162:165], v[180:183], v[124:127]
	v_mfma_f32_16x16x32_bf16 v[116:119], v[172:175], v[180:183], v[116:119]
	v_mfma_f32_16x16x32_bf16 v[108:111], v[162:165], v[188:191], v[108:111]
	v_mfma_f32_16x16x32_bf16 v[100:103], v[172:175], v[188:191], v[100:103]
	v_mfma_f32_16x16x32_bf16 v[92:95], v[162:165], v[200:203], v[92:95]
	v_mfma_f32_16x16x32_bf16 v[84:87], v[172:175], v[200:203], v[84:87]
	v_mfma_f32_16x16x32_bf16 v[60:63], v[162:165], v[208:211], v[60:63]
	v_mfma_f32_16x16x32_bf16 v[52:55], v[172:175], v[208:211], v[52:55]
	v_mfma_f32_16x16x32_bf16 v[124:127], v[166:169], v[184:187], v[124:127]
	v_mfma_f32_16x16x32_bf16 v[116:119], v[176:179], v[184:187], v[116:119]
	v_mfma_f32_16x16x32_bf16 v[108:111], v[166:169], v[196:199], v[108:111]
	v_mfma_f32_16x16x32_bf16 v[100:103], v[176:179], v[196:199], v[100:103]
	v_mfma_f32_16x16x32_bf16 v[92:95], v[166:169], v[204:207], v[92:95]
	v_mfma_f32_16x16x32_bf16 v[84:87], v[176:179], v[204:207], v[84:87]
	v_mfma_f32_16x16x32_bf16 v[60:63], v[166:169], v[212:215], v[60:63]
	v_mfma_f32_16x16x32_bf16 v[52:55], v[176:179], v[212:215], v[52:55]
	s_barrier
	s_setprio 0
	ds_read_b128 v[180:183], v141 offset:16384
	ds_read_b128 v[184:187], v141 offset:17408
	ds_read_b128 v[188:191], v141 offset:18432
	ds_read_b128 v[196:199], v141 offset:19456
	ds_read_b128 v[200:203], v141 offset:20480
	ds_read_b128 v[204:207], v141 offset:21504
	ds_read_b128 v[208:211], v141 offset:22528
	ds_read_b128 v[212:215], v141 offset:23552
	s_add_i32 m0, s16, 0x10000
	s_nop 0
	global_load_lds_dwordx4 v1, s[84:85]
	s_nop 0
	s_add_i32 m0, s16, 0x12000
	s_nop 0
	global_load_lds_dwordx4 v134, s[84:85]
	s_add_u32 s52, s84, 0x40000
	s_addc_u32 s53, s85, 0
	s_add_i32 m0, s16, 0x14000
	s_nop 0
	global_load_lds_dwordx4 v1, s[52:53]
	s_nop 0
	s_add_i32 m0, s16, 0x16000
	s_nop 0
	global_load_lds_dwordx4 v134, s[52:53]
	s_nop 0
	s_add_i32 m0, s16, 0
	s_nop 0
	global_load_lds_dwordx4 v136, s[90:91]
	s_nop 0
	s_add_i32 m0, s16, 0x2000
	s_nop 0
	global_load_lds_dwordx4 v137, s[90:91]
	s_waitcnt vmcnt(8)
	s_waitcnt lgkmcnt(0)
	s_setprio 1
	s_barrier
	v_mfma_f32_16x16x32_bf16 v[80:83], v[146:149], v[180:183], v[80:83]
	v_mfma_f32_16x16x32_bf16 v[72:75], v[154:157], v[180:183], v[72:75]
	v_mfma_f32_16x16x32_bf16 v[48:51], v[146:149], v[188:191], v[48:51]
	v_mfma_f32_16x16x32_bf16 v[40:43], v[154:157], v[188:191], v[40:43]
	v_mfma_f32_16x16x32_bf16 v[32:35], v[146:149], v[200:203], v[32:35]
	v_mfma_f32_16x16x32_bf16 v[24:27], v[154:157], v[200:203], v[24:27]
	v_mfma_f32_16x16x32_bf16 v[16:19], v[146:149], v[208:211], v[16:19]
	v_mfma_f32_16x16x32_bf16 v[8:11], v[154:157], v[208:211], v[8:11]
	v_mfma_f32_16x16x32_bf16 v[80:83], v[150:153], v[184:187], v[80:83]
	v_mfma_f32_16x16x32_bf16 v[72:75], v[158:161], v[184:187], v[72:75]
	v_mfma_f32_16x16x32_bf16 v[48:51], v[150:153], v[196:199], v[48:51]
	v_mfma_f32_16x16x32_bf16 v[40:43], v[158:161], v[196:199], v[40:43]
	v_mfma_f32_16x16x32_bf16 v[32:35], v[150:153], v[204:207], v[32:35]
	v_mfma_f32_16x16x32_bf16 v[24:27], v[158:161], v[204:207], v[24:27]
	v_mfma_f32_16x16x32_bf16 v[16:19], v[150:153], v[212:215], v[16:19]
	v_mfma_f32_16x16x32_bf16 v[8:11], v[158:161], v[212:215], v[8:11]
	v_mfma_f32_16x16x32_bf16 v[76:79], v[162:165], v[180:183], v[76:79]
	v_mfma_f32_16x16x32_bf16 v[68:71], v[172:175], v[180:183], v[68:71]
	v_mfma_f32_16x16x32_bf16 v[44:47], v[162:165], v[188:191], v[44:47]
	v_mfma_f32_16x16x32_bf16 v[36:39], v[172:175], v[188:191], v[36:39]
	v_mfma_f32_16x16x32_bf16 v[28:31], v[162:165], v[200:203], v[28:31]
	v_mfma_f32_16x16x32_bf16 v[20:23], v[172:175], v[200:203], v[20:23]
	v_mfma_f32_16x16x32_bf16 v[12:15], v[162:165], v[208:211], v[12:15]
	v_mfma_f32_16x16x32_bf16 v[4:7], v[172:175], v[208:211], v[4:7]
	v_mfma_f32_16x16x32_bf16 v[76:79], v[166:169], v[184:187], v[76:79]
	v_mfma_f32_16x16x32_bf16 v[68:71], v[176:179], v[184:187], v[68:71]
	v_mfma_f32_16x16x32_bf16 v[44:47], v[166:169], v[196:199], v[44:47]
	v_mfma_f32_16x16x32_bf16 v[36:39], v[176:179], v[196:199], v[36:39]
	v_mfma_f32_16x16x32_bf16 v[28:31], v[166:169], v[204:207], v[28:31]
	v_mfma_f32_16x16x32_bf16 v[20:23], v[176:179], v[204:207], v[20:23]
	v_mfma_f32_16x16x32_bf16 v[12:15], v[166:169], v[212:215], v[12:15]
	v_mfma_f32_16x16x32_bf16 v[4:7], v[176:179], v[212:215], v[4:7]
	s_barrier
	s_setprio 0
	ds_read_b128 v[146:149], v144
	ds_read_b128 v[150:153], v144 offset:1024
	ds_read_b128 v[154:157], v144 offset:2048
	ds_read_b128 v[158:161], v144 offset:3072
	ds_read_b128 v[162:165], v145
	ds_read_b128 v[166:169], v145 offset:1024
	ds_read_b128 v[172:175], v145 offset:2048
	ds_read_b128 v[176:179], v145 offset:3072
	ds_read_b128 v[180:183], v141 offset:32768
	ds_read_b128 v[184:187], v141 offset:33792
	ds_read_b128 v[188:191], v141 offset:34816
	ds_read_b128 v[196:199], v141 offset:35840
	ds_read_b128 v[200:203], v141 offset:36864
	ds_read_b128 v[204:207], v141 offset:37888
	ds_read_b128 v[208:211], v141 offset:38912
	ds_read_b128 v[212:215], v141 offset:39936
	s_add_u32 s52, s90, 0x40000
	s_addc_u32 s53, s91, 0
	s_add_i32 m0, s16, 0x4000
	s_nop 0
	global_load_lds_dwordx4 v136, s[52:53]
	s_nop 0
	s_add_i32 m0, s16, 0x6000
	s_nop 0
	global_load_lds_dwordx4 v137, s[52:53]
	s_waitcnt vmcnt(8)
	s_waitcnt lgkmcnt(0)
	s_setprio 1
	s_barrier
	v_mfma_f32_16x16x32_bf16 v[128:131], v[146:149], v[180:183], v[128:131]
	v_mfma_f32_16x16x32_bf16 v[120:123], v[154:157], v[180:183], v[120:123]
	v_mfma_f32_16x16x32_bf16 v[112:115], v[146:149], v[188:191], v[112:115]
	v_mfma_f32_16x16x32_bf16 v[104:107], v[154:157], v[188:191], v[104:107]
	v_mfma_f32_16x16x32_bf16 v[96:99], v[146:149], v[200:203], v[96:99]
	v_mfma_f32_16x16x32_bf16 v[88:91], v[154:157], v[200:203], v[88:91]
	v_mfma_f32_16x16x32_bf16 v[64:67], v[146:149], v[208:211], v[64:67]
	v_mfma_f32_16x16x32_bf16 v[56:59], v[154:157], v[208:211], v[56:59]
	v_mfma_f32_16x16x32_bf16 v[128:131], v[150:153], v[184:187], v[128:131]
	v_mfma_f32_16x16x32_bf16 v[120:123], v[158:161], v[184:187], v[120:123]
	v_mfma_f32_16x16x32_bf16 v[112:115], v[150:153], v[196:199], v[112:115]
	v_mfma_f32_16x16x32_bf16 v[104:107], v[158:161], v[196:199], v[104:107]
	v_mfma_f32_16x16x32_bf16 v[96:99], v[150:153], v[204:207], v[96:99]
	v_mfma_f32_16x16x32_bf16 v[88:91], v[158:161], v[204:207], v[88:91]
	v_mfma_f32_16x16x32_bf16 v[64:67], v[150:153], v[212:215], v[64:67]
	v_mfma_f32_16x16x32_bf16 v[56:59], v[158:161], v[212:215], v[56:59]
	v_mfma_f32_16x16x32_bf16 v[124:127], v[162:165], v[180:183], v[124:127]
	v_mfma_f32_16x16x32_bf16 v[116:119], v[172:175], v[180:183], v[116:119]
	v_mfma_f32_16x16x32_bf16 v[108:111], v[162:165], v[188:191], v[108:111]
	v_mfma_f32_16x16x32_bf16 v[100:103], v[172:175], v[188:191], v[100:103]
	v_mfma_f32_16x16x32_bf16 v[92:95], v[162:165], v[200:203], v[92:95]
	v_mfma_f32_16x16x32_bf16 v[84:87], v[172:175], v[200:203], v[84:87]
	v_mfma_f32_16x16x32_bf16 v[60:63], v[162:165], v[208:211], v[60:63]
	v_mfma_f32_16x16x32_bf16 v[52:55], v[172:175], v[208:211], v[52:55]
	v_mfma_f32_16x16x32_bf16 v[124:127], v[166:169], v[184:187], v[124:127]
	v_mfma_f32_16x16x32_bf16 v[116:119], v[176:179], v[184:187], v[116:119]
	v_mfma_f32_16x16x32_bf16 v[108:111], v[166:169], v[196:199], v[108:111]
	v_mfma_f32_16x16x32_bf16 v[100:103], v[176:179], v[196:199], v[100:103]
	v_mfma_f32_16x16x32_bf16 v[92:95], v[166:169], v[204:207], v[92:95]
	v_mfma_f32_16x16x32_bf16 v[84:87], v[176:179], v[204:207], v[84:87]
	v_mfma_f32_16x16x32_bf16 v[60:63], v[166:169], v[212:215], v[60:63]
	v_mfma_f32_16x16x32_bf16 v[52:55], v[176:179], v[212:215], v[52:55]
	s_barrier
	s_setprio 0
	ds_read_b128 v[180:183], v141 offset:49152
	ds_read_b128 v[184:187], v141 offset:50176
	ds_read_b128 v[188:191], v141 offset:51200
	ds_read_b128 v[196:199], v141 offset:52224
	ds_read_b128 v[200:203], v141 offset:53248
	ds_read_b128 v[204:207], v141 offset:54272
	ds_read_b128 v[208:211], v141 offset:55296
	ds_read_b128 v[212:215], v141 offset:56320
	s_add_i32 m0, s16, 0x18000
	s_nop 0
	global_load_lds_dwordx4 v1, s[88:89]
	s_nop 0
	s_add_i32 m0, s16, 0x1a000
	s_nop 0
	global_load_lds_dwordx4 v134, s[88:89]
	s_add_u32 s52, s84, 0x40080
	s_addc_u32 s53, s85, 0
	s_add_i32 m0, s16, 0x1c000
	s_nop 0
	global_load_lds_dwordx4 v1, s[52:53]
	s_nop 0
	s_add_i32 m0, s16, 0x1e000
	s_nop 0
	global_load_lds_dwordx4 v134, s[52:53]
	s_nop 0
	s_add_i32 m0, s16, 0x8000
	s_nop 0
	global_load_lds_dwordx4 v136, s[86:87]
	s_nop 0
	s_add_i32 m0, s16, 0xa000
	s_nop 0
	global_load_lds_dwordx4 v137, s[86:87]
	s_waitcnt vmcnt(8)
	s_waitcnt lgkmcnt(0)
	s_setprio 1
	s_barrier
	v_mfma_f32_16x16x32_bf16 v[80:83], v[146:149], v[180:183], v[80:83]
	v_mfma_f32_16x16x32_bf16 v[72:75], v[154:157], v[180:183], v[72:75]
	v_mfma_f32_16x16x32_bf16 v[48:51], v[146:149], v[188:191], v[48:51]
	v_mfma_f32_16x16x32_bf16 v[40:43], v[154:157], v[188:191], v[40:43]
	v_mfma_f32_16x16x32_bf16 v[32:35], v[146:149], v[200:203], v[32:35]
	v_mfma_f32_16x16x32_bf16 v[24:27], v[154:157], v[200:203], v[24:27]
	v_mfma_f32_16x16x32_bf16 v[16:19], v[146:149], v[208:211], v[16:19]
	v_mfma_f32_16x16x32_bf16 v[8:11], v[154:157], v[208:211], v[8:11]
	v_mfma_f32_16x16x32_bf16 v[80:83], v[150:153], v[184:187], v[80:83]
	v_mfma_f32_16x16x32_bf16 v[72:75], v[158:161], v[184:187], v[72:75]
	v_mfma_f32_16x16x32_bf16 v[48:51], v[150:153], v[196:199], v[48:51]
	v_mfma_f32_16x16x32_bf16 v[40:43], v[158:161], v[196:199], v[40:43]
	v_mfma_f32_16x16x32_bf16 v[32:35], v[150:153], v[204:207], v[32:35]
	v_mfma_f32_16x16x32_bf16 v[24:27], v[158:161], v[204:207], v[24:27]
	v_mfma_f32_16x16x32_bf16 v[16:19], v[150:153], v[212:215], v[16:19]
	v_mfma_f32_16x16x32_bf16 v[8:11], v[158:161], v[212:215], v[8:11]
	v_mfma_f32_16x16x32_bf16 v[76:79], v[162:165], v[180:183], v[76:79]
	v_mfma_f32_16x16x32_bf16 v[68:71], v[172:175], v[180:183], v[68:71]
	v_mfma_f32_16x16x32_bf16 v[44:47], v[162:165], v[188:191], v[44:47]
	v_mfma_f32_16x16x32_bf16 v[36:39], v[172:175], v[188:191], v[36:39]
	v_mfma_f32_16x16x32_bf16 v[28:31], v[162:165], v[200:203], v[28:31]
	v_mfma_f32_16x16x32_bf16 v[20:23], v[172:175], v[200:203], v[20:23]
	v_mfma_f32_16x16x32_bf16 v[12:15], v[162:165], v[208:211], v[12:15]
	v_mfma_f32_16x16x32_bf16 v[4:7], v[172:175], v[208:211], v[4:7]
	v_mfma_f32_16x16x32_bf16 v[76:79], v[166:169], v[184:187], v[76:79]
	v_mfma_f32_16x16x32_bf16 v[68:71], v[176:179], v[184:187], v[68:71]
	v_mfma_f32_16x16x32_bf16 v[44:47], v[166:169], v[196:199], v[44:47]
	v_mfma_f32_16x16x32_bf16 v[36:39], v[176:179], v[196:199], v[36:39]
	v_mfma_f32_16x16x32_bf16 v[28:31], v[166:169], v[204:207], v[28:31]
	v_mfma_f32_16x16x32_bf16 v[20:23], v[176:179], v[204:207], v[20:23]
	v_mfma_f32_16x16x32_bf16 v[12:15], v[166:169], v[212:215], v[12:15]
	v_mfma_f32_16x16x32_bf16 v[4:7], v[176:179], v[212:215], v[4:7]
	s_barrier
	s_setprio 0
	s_add_i32 s52, s41, 2
	s_cmp_gt_u32 s41, 13
	s_cbranch_scc1 .LBB0_404
	s_mov_b32 s41, s52
	s_branch .LBB0_383

.LBB0_728:
	v_add_u32_e32 v137, 0x10000, v2
	v_add_u32_e32 v138, 0x14000, v2
	s_and_b64 s[2:3], exec, s[84:85]
	ds_read_b128 v[4:7], v137
	ds_read_b128 v[8:11], v137 offset:1024
	ds_read_b128 v[12:15], v137 offset:2048
	ds_read_b128 v[16:19], v137 offset:3072
	ds_read_b128 v[20:23], v138
	ds_read_b128 v[24:27], v138 offset:1024
	ds_read_b128 v[28:31], v138 offset:2048
	ds_read_b128 v[32:35], v138 offset:3072
	s_cselect_b32 s47, s6, s29
	s_add_u32 s12, s78, 0x100
	s_addc_u32 s13, s79, 0
	s_add_u32 s2, s78, 0x180
	s_addc_u32 s3, s79, 0
	s_add_u32 s6, s76, 0x100
	s_addc_u32 s7, s77, 0
	ds_read_b128 v[36:39], v136
	ds_read_b128 v[40:43], v136 offset:1024
	ds_read_b128 v[44:47], v136 offset:2048
	ds_read_b128 v[48:51], v136 offset:3072
	ds_read_b128 v[52:55], v136 offset:4096
	ds_read_b128 v[56:59], v136 offset:5120
	ds_read_b128 v[60:63], v136 offset:6144
	ds_read_b128 v[64:67], v136 offset:7168
	s_add_u32 s59, s78, s16
	s_addc_u32 s38, s79, 0
	s_add_u32 s26, s59, 0x80
	s_addc_u32 s27, s38, 0
	s_add_i32 m0, s43, 0xc000
	s_nop 0
	global_load_lds_dwordx4 v134, s[26:27]
	s_nop 0
	s_add_i32 m0, s43, 0xe000
	s_nop 0
	global_load_lds_dwordx4 v135, s[26:27]
	s_waitcnt vmcnt(8)
	s_waitcnt lgkmcnt(0)
	s_setprio 1
	s_barrier
	v_mfma_f32_16x16x32_bf16 v[86:89], v[4:7], v[52:55], 0
	v_mfma_f32_16x16x32_bf16 v[94:97], v[8:11], v[56:59], v[86:89]
	v_mfma_f32_16x16x32_bf16 v[86:89], v[12:15], v[52:55], 0
	v_mfma_f32_16x16x32_bf16 v[98:101], v[16:19], v[56:59], v[86:89]
	v_mfma_f32_16x16x32_bf16 v[86:89], v[4:7], v[60:63], 0
	v_mfma_f32_16x16x32_bf16 v[68:71], v[4:7], v[36:39], 0
	v_mfma_f32_16x16x32_bf16 v[72:75], v[12:15], v[36:39], 0
	v_mfma_f32_16x16x32_bf16 v[78:81], v[4:7], v[44:47], 0
	v_mfma_f32_16x16x32_bf16 v[82:85], v[12:15], v[44:47], 0
	v_mfma_f32_16x16x32_bf16 v[102:105], v[8:11], v[64:67], v[86:89]
	v_mfma_f32_16x16x32_bf16 v[86:89], v[12:15], v[60:63], 0
	v_mfma_f32_16x16x32_bf16 v[68:71], v[8:11], v[40:43], v[68:71]
	v_mfma_f32_16x16x32_bf16 v[74:77], v[16:19], v[40:43], v[72:75]
	v_mfma_f32_16x16x32_bf16 v[78:81], v[8:11], v[48:51], v[78:81]
	v_mfma_f32_16x16x32_bf16 v[82:85], v[16:19], v[48:51], v[82:85]
	v_mfma_f32_16x16x32_bf16 v[106:109], v[16:19], v[64:67], v[86:89]
	v_mfma_f32_16x16x32_bf16 v[86:89], v[20:23], v[36:39], 0
	v_mfma_f32_16x16x32_bf16 v[36:39], v[28:31], v[36:39], 0
	v_mfma_f32_16x16x32_bf16 v[110:113], v[24:27], v[40:43], v[86:89]
	v_mfma_f32_16x16x32_bf16 v[36:39], v[32:35], v[40:43], v[36:39]
	v_mfma_f32_16x16x32_bf16 v[40:43], v[20:23], v[44:47], 0
	v_mfma_f32_16x16x32_bf16 v[44:47], v[28:31], v[44:47], 0
	v_mfma_f32_16x16x32_bf16 v[40:43], v[24:27], v[48:51], v[40:43]
	v_mfma_f32_16x16x32_bf16 v[44:47], v[32:35], v[48:51], v[44:47]
	v_mfma_f32_16x16x32_bf16 v[48:51], v[20:23], v[52:55], 0
	v_mfma_f32_16x16x32_bf16 v[52:55], v[28:31], v[52:55], 0
	v_mfma_f32_16x16x32_bf16 v[48:51], v[24:27], v[56:59], v[48:51]
	v_mfma_f32_16x16x32_bf16 v[52:55], v[32:35], v[56:59], v[52:55]
	v_mfma_f32_16x16x32_bf16 v[56:59], v[20:23], v[60:63], 0
	v_mfma_f32_16x16x32_bf16 v[60:63], v[28:31], v[60:63], 0
	v_mfma_f32_16x16x32_bf16 v[56:59], v[24:27], v[64:67], v[56:59]
	v_mfma_f32_16x16x32_bf16 v[60:63], v[32:35], v[64:67], v[60:63]
	s_barrier
	s_setprio 0
	ds_read_b128 v[64:67], v136 offset:16384
	ds_read_b128 v[86:89], v136 offset:17408
	ds_read_b128 v[90:93], v136 offset:18432
	ds_read_b128 v[114:117], v136 offset:19456
	ds_read_b128 v[118:121], v136 offset:20480
	ds_read_b128 v[122:125], v136 offset:21504
	ds_read_b128 v[126:129], v136 offset:22528
	ds_read_b128 v[130:133], v136 offset:23552
	s_add_i32 m0, s43, 0x10000
	s_nop 0
	global_load_lds_dwordx4 v134, s[6:7]
	s_nop 0
	s_add_i32 m0, s43, 0x12000
	s_nop 0
	global_load_lds_dwordx4 v135, s[6:7]
	s_add_u32 s6, s6, s16
	s_addc_u32 s7, s7, 0
	s_add_i32 m0, s43, 0x14000
	s_nop 0
	global_load_lds_dwordx4 v134, s[6:7]
	s_nop 0
	s_add_i32 m0, s43, 0x16000
	s_nop 0
	global_load_lds_dwordx4 v135, s[6:7]
	s_nop 0
	s_add_i32 m0, s43, 0
	s_nop 0
	global_load_lds_dwordx4 v134, s[12:13]
	s_nop 0
	s_add_i32 m0, s43, 0x2000
	s_nop 0
	global_load_lds_dwordx4 v135, s[12:13]
	s_waitcnt vmcnt(8)
	s_waitcnt lgkmcnt(0)
	s_setprio 1
	s_barrier
	v_mfma_f32_16x16x32_bf16 v[140:143], v[4:7], v[64:67], 0
	v_mfma_f32_16x16x32_bf16 v[150:153], v[4:7], v[90:93], 0
	v_mfma_f32_16x16x32_bf16 v[158:161], v[4:7], v[118:121], 0
	v_mfma_f32_16x16x32_bf16 v[4:7], v[4:7], v[126:129], 0
	v_mfma_f32_16x16x32_bf16 v[146:149], v[12:15], v[64:67], 0
	v_mfma_f32_16x16x32_bf16 v[154:157], v[12:15], v[90:93], 0
	v_mfma_f32_16x16x32_bf16 v[162:165], v[12:15], v[118:121], 0
	v_mfma_f32_16x16x32_bf16 v[166:169], v[8:11], v[130:133], v[4:7]
	v_mfma_f32_16x16x32_bf16 v[4:7], v[12:15], v[126:129], 0
	v_mfma_f32_16x16x32_bf16 v[142:145], v[8:11], v[86:89], v[140:143]
	v_mfma_f32_16x16x32_bf16 v[146:149], v[16:19], v[86:89], v[146:149]
	v_mfma_f32_16x16x32_bf16 v[150:153], v[8:11], v[114:117], v[150:153]
	v_mfma_f32_16x16x32_bf16 v[154:157], v[16:19], v[114:117], v[154:157]
	v_mfma_f32_16x16x32_bf16 v[158:161], v[8:11], v[122:125], v[158:161]
	v_mfma_f32_16x16x32_bf16 v[162:165], v[16:19], v[122:125], v[162:165]
	v_mfma_f32_16x16x32_bf16 v[172:175], v[16:19], v[130:133], v[4:7]
	v_mfma_f32_16x16x32_bf16 v[4:7], v[20:23], v[64:67], 0
	v_mfma_f32_16x16x32_bf16 v[176:179], v[24:27], v[86:89], v[4:7]
	v_mfma_f32_16x16x32_bf16 v[4:7], v[28:31], v[64:67], 0
	v_mfma_f32_16x16x32_bf16 v[64:67], v[32:35], v[86:89], v[4:7]
	v_mfma_f32_16x16x32_bf16 v[4:7], v[20:23], v[90:93], 0
	v_mfma_f32_16x16x32_bf16 v[180:183], v[24:27], v[114:117], v[4:7]
	v_mfma_f32_16x16x32_bf16 v[4:7], v[28:31], v[90:93], 0
	v_mfma_f32_16x16x32_bf16 v[184:187], v[32:35], v[114:117], v[4:7]
	v_mfma_f32_16x16x32_bf16 v[4:7], v[20:23], v[118:121], 0
	v_mfma_f32_16x16x32_bf16 v[196:199], v[24:27], v[122:125], v[4:7]
	v_mfma_f32_16x16x32_bf16 v[4:7], v[28:31], v[118:121], 0
	v_mfma_f32_16x16x32_bf16 v[200:203], v[32:35], v[122:125], v[4:7]
	v_mfma_f32_16x16x32_bf16 v[4:7], v[20:23], v[126:129], 0
	v_mfma_f32_16x16x32_bf16 v[204:207], v[24:27], v[130:133], v[4:7]
	v_mfma_f32_16x16x32_bf16 v[4:7], v[28:31], v[126:129], 0
	v_mfma_f32_16x16x32_bf16 v[208:211], v[32:35], v[130:133], v[4:7]
	s_barrier
	s_setprio 0
	v_add_u32_e32 v139, 0x18000, v2
	v_add_u32_e32 v140, 0x1c000, v2
	ds_read_b128 v[18:21], v139
	ds_read_b128 v[212:215], v139 offset:1024
	ds_read_b128 v[216:219], v139 offset:2048
	ds_read_b128 v[220:223], v139 offset:3072
	ds_read_b128 v[224:227], v140
	ds_read_b128 v[228:231], v140 offset:1024
	ds_read_b128 v[232:235], v140 offset:2048
	ds_read_b128 v[236:239], v140 offset:3072
	ds_read_b128 v[4:7], v136 offset:32768
	ds_read_b128 v[8:11], v136 offset:33792
	ds_read_b128 v[12:15], v136 offset:34816
	ds_read_b128 v[22:25], v136 offset:35840
	ds_read_b128 v[26:29], v136 offset:36864
	ds_read_b128 v[30:33], v136 offset:37888
	ds_read_b128 v[130:133], v136 offset:38912
	ds_read_b128 v[240:243], v136 offset:39936
	s_add_u32 s6, s12, s16
	s_addc_u32 s7, s13, 0
	s_add_i32 m0, s43, 0x4000
	s_nop 0
	global_load_lds_dwordx4 v134, s[6:7]
	s_nop 0
	s_add_i32 m0, s43, 0x6000
	s_nop 0
	global_load_lds_dwordx4 v135, s[6:7]
	s_waitcnt vmcnt(8)
	s_waitcnt lgkmcnt(0)
	s_setprio 1
	s_barrier
	v_mfma_f32_16x16x32_bf16 v[74:77], v[216:219], v[4:7], v[74:77]
	v_mfma_f32_16x16x32_bf16 v[86:89], v[220:223], v[8:11], v[74:77]
	v_mfma_f32_16x16x32_bf16 v[74:77], v[18:21], v[12:15], v[78:81]
	v_mfma_f32_16x16x32_bf16 v[78:81], v[216:219], v[12:15], v[82:85]
	v_mfma_f32_16x16x32_bf16 v[82:85], v[216:219], v[26:29], v[98:101]
	v_mfma_f32_16x16x32_bf16 v[68:71], v[18:21], v[4:7], v[68:71]
	v_mfma_f32_16x16x32_bf16 v[90:93], v[220:223], v[22:25], v[78:81]
	v_mfma_f32_16x16x32_bf16 v[78:81], v[18:21], v[26:29], v[94:97]
	v_mfma_f32_16x16x32_bf16 v[94:97], v[220:223], v[30:33], v[82:85]
	v_mfma_f32_16x16x32_bf16 v[82:85], v[18:21], v[130:133], v[102:105]
	v_mfma_f32_16x16x32_bf16 v[98:101], v[216:219], v[130:133], v[106:109]
	v_mfma_f32_16x16x32_bf16 v[70:73], v[212:215], v[8:11], v[68:71]
	v_mfma_f32_16x16x32_bf16 v[74:77], v[212:215], v[22:25], v[74:77]
	v_mfma_f32_16x16x32_bf16 v[78:81], v[212:215], v[30:33], v[78:81]
	v_mfma_f32_16x16x32_bf16 v[82:85], v[212:215], v[240:243], v[82:85]
	v_mfma_f32_16x16x32_bf16 v[98:101], v[220:223], v[240:243], v[98:101]
	v_mfma_f32_16x16x32_bf16 v[102:105], v[224:227], v[4:7], v[110:113]
	v_mfma_f32_16x16x32_bf16 v[4:7], v[232:235], v[4:7], v[36:39]
	v_mfma_f32_16x16x32_bf16 v[118:121], v[236:239], v[8:11], v[4:7]
	v_mfma_f32_16x16x32_bf16 v[4:7], v[224:227], v[12:15], v[40:43]
	v_mfma_f32_16x16x32_bf16 v[106:109], v[228:231], v[22:25], v[4:7]
	v_mfma_f32_16x16x32_bf16 v[4:7], v[232:235], v[12:15], v[44:47]
	v_mfma_f32_16x16x32_bf16 v[122:125], v[236:239], v[22:25], v[4:7]
	v_mfma_f32_16x16x32_bf16 v[4:7], v[224:227], v[26:29], v[48:51]
	v_mfma_f32_16x16x32_bf16 v[110:113], v[228:231], v[30:33], v[4:7]
	v_mfma_f32_16x16x32_bf16 v[4:7], v[232:235], v[26:29], v[52:55]
	v_mfma_f32_16x16x32_bf16 v[126:129], v[236:239], v[30:33], v[4:7]
	v_mfma_f32_16x16x32_bf16 v[4:7], v[224:227], v[130:133], v[56:59]
	v_mfma_f32_16x16x32_bf16 v[114:117], v[228:231], v[240:243], v[4:7]
	v_mfma_f32_16x16x32_bf16 v[4:7], v[232:235], v[130:133], v[60:63]
	v_mfma_f32_16x16x32_bf16 v[102:105], v[228:231], v[8:11], v[102:105]
	v_mfma_f32_16x16x32_bf16 v[130:133], v[236:239], v[240:243], v[4:7]
	s_barrier
	s_setprio 0
	s_add_u32 s6, s76, 0x180
	ds_read_b128 v[42:45], v136 offset:49152
	ds_read_b128 v[46:49], v136 offset:50176
	ds_read_b128 v[50:53], v136 offset:51200
	ds_read_b128 v[58:61], v136 offset:52224
	ds_read_b128 v[240:243], v136 offset:53248
	ds_read_b128 v[244:247], v136 offset:54272
	ds_read_b128 v[248:251], v136 offset:55296
	ds_read_b128 v[188:191], v136 offset:56320
	s_addc_u32 s7, s77, 0
	s_add_i32 m0, s43, 0x18000
	s_nop 0
	global_load_lds_dwordx4 v134, s[6:7]
	s_nop 0
	s_add_i32 m0, s43, 0x1a000
	s_nop 0
	global_load_lds_dwordx4 v135, s[6:7]
	s_add_u32 s6, s6, s16
	s_addc_u32 s7, s7, 0
	s_add_i32 m0, s43, 0x1c000
	s_nop 0
	global_load_lds_dwordx4 v134, s[6:7]
	s_nop 0
	s_add_i32 m0, s43, 0x1e000
	s_nop 0
	global_load_lds_dwordx4 v135, s[6:7]
	s_nop 0
	s_add_i32 m0, s43, 0x8000
	s_nop 0
	global_load_lds_dwordx4 v134, s[2:3]
	s_nop 0
	s_add_i32 m0, s43, 0xa000
	s_nop 0
	global_load_lds_dwordx4 v135, s[2:3]
	s_waitcnt vmcnt(8)
	s_waitcnt lgkmcnt(0)
	s_setprio 1
	s_barrier
	v_mfma_f32_16x16x32_bf16 v[10:13], v[216:219], v[42:45], v[146:149]
	v_mfma_f32_16x16x32_bf16 v[14:17], v[216:219], v[50:53], v[154:157]
	v_mfma_f32_16x16x32_bf16 v[4:7], v[18:21], v[42:45], v[142:145]
	v_mfma_f32_16x16x32_bf16 v[22:25], v[220:223], v[46:49], v[10:13]
	v_mfma_f32_16x16x32_bf16 v[10:13], v[18:21], v[50:53], v[150:153]
	v_mfma_f32_16x16x32_bf16 v[26:29], v[220:223], v[58:61], v[14:17]
	v_mfma_f32_16x16x32_bf16 v[14:17], v[18:21], v[240:243], v[158:161]
	v_mfma_f32_16x16x32_bf16 v[30:33], v[216:219], v[240:243], v[162:165]
	v_mfma_f32_16x16x32_bf16 v[18:21], v[18:21], v[248:251], v[166:169]
	v_mfma_f32_16x16x32_bf16 v[34:37], v[216:219], v[248:251], v[172:175]
	v_mfma_f32_16x16x32_bf16 v[6:9], v[212:215], v[46:49], v[4:7]
	v_mfma_f32_16x16x32_bf16 v[10:13], v[212:215], v[58:61], v[10:13]
	v_mfma_f32_16x16x32_bf16 v[14:17], v[212:215], v[244:247], v[14:17]
	v_mfma_f32_16x16x32_bf16 v[30:33], v[220:223], v[244:247], v[30:33]
	v_mfma_f32_16x16x32_bf16 v[18:21], v[212:215], v[188:191], v[18:21]
	v_mfma_f32_16x16x32_bf16 v[34:37], v[220:223], v[188:191], v[34:37]
	v_mfma_f32_16x16x32_bf16 v[38:41], v[224:227], v[42:45], v[176:179]
	v_mfma_f32_16x16x32_bf16 v[42:45], v[232:235], v[42:45], v[64:67]
	v_mfma_f32_16x16x32_bf16 v[38:41], v[228:231], v[46:49], v[38:41]
	v_mfma_f32_16x16x32_bf16 v[54:57], v[236:239], v[46:49], v[42:45]
	v_mfma_f32_16x16x32_bf16 v[42:45], v[224:227], v[50:53], v[180:183]
	v_mfma_f32_16x16x32_bf16 v[46:49], v[232:235], v[50:53], v[184:187]
	v_mfma_f32_16x16x32_bf16 v[50:53], v[232:235], v[240:243], v[200:203]
	v_mfma_f32_16x16x32_bf16 v[42:45], v[228:231], v[58:61], v[42:45]
	v_mfma_f32_16x16x32_bf16 v[58:61], v[236:239], v[58:61], v[46:49]
	v_mfma_f32_16x16x32_bf16 v[46:49], v[224:227], v[240:243], v[196:199]
	v_mfma_f32_16x16x32_bf16 v[62:65], v[236:239], v[244:247], v[50:53]
	v_mfma_f32_16x16x32_bf16 v[50:53], v[224:227], v[248:251], v[204:207]
	v_mfma_f32_16x16x32_bf16 v[66:69], v[232:235], v[248:251], v[208:211]
	v_mfma_f32_16x16x32_bf16 v[46:49], v[228:231], v[244:247], v[46:49]
	v_mfma_f32_16x16x32_bf16 v[50:53], v[228:231], v[188:191], v[50:53]
	v_mfma_f32_16x16x32_bf16 v[66:69], v[236:239], v[188:191], v[66:69]
	s_barrier
	s_setprio 0
	s_add_i32 s2, s47, 1
	s_lshl_b32 s72, s47, 6
	s_and_b32 s3, s2, 31
	s_lshl_b32 s2, s2, 6
	s_add_i32 s6, s72, 0x9000
	s_add_i32 s7, s72, 0x8000
	s_add_i32 s18, s72, 0x7000
	s_addk_i32 s2, 0x6000
	s_cmp_eq_u32 s3, 0
	s_cselect_b32 s26, 0, 32
	s_cselect_b32 s27, 0, s2
	s_add_i32 s40, s72, 0x6000
	s_add_i32 s41, s72, 0x5000
	s_and_b32 s2, s47, 31
	s_add_i32 s3, s72, 0x4fc0
	s_cmp_eq_u32 s2, 0
	s_cselect_b32 s50, 0, 0x48
	s_cselect_b32 s52, 0, s3
	s_add_i32 s58, s72, 0x4000
	s_addk_i32 s72, 0x3000
	s_mov_b32 s90, 2
	s_branch .LBB0_731

.LBB0_730:
	s_or_b32 s20, s90, 1
	s_add_i32 s90, s90, 2
	s_mov_b32 s91, s21
	ds_read_b128 v[142:145], v137
	ds_read_b128 v[146:149], v137 offset:1024
	ds_read_b128 v[150:153], v137 offset:2048
	ds_read_b128 v[154:157], v137 offset:3072
	ds_read_b128 v[158:161], v138
	ds_read_b128 v[162:165], v138 offset:1024
	ds_read_b128 v[166:169], v138 offset:2048
	ds_read_b128 v[172:175], v138 offset:3072
	s_lshl_b64 s[96:97], s[20:21], 7
	s_lshl_b64 s[2:3], s[90:91], 7
	s_add_u32 s20, s78, s2
	s_addc_u32 s73, s79, s3
	s_and_b64 s[12:13], s[92:93], exec
	s_cselect_b32 s95, s73, s87
	s_cselect_b32 s94, s20, s86
	s_add_u32 s12, s76, s2
	s_addc_u32 s13, s77, s3
	s_and_b64 s[2:3], s[92:93], exec
	s_cselect_b32 s93, s13, s89
	s_cselect_b32 s92, s12, s88
	s_add_u32 s2, s94, 0x80
	s_addc_u32 s3, s95, 0
	s_add_u32 s12, s92, 0x80
	s_addc_u32 s13, s93, 0
	ds_read_b128 v[176:179], v136
	ds_read_b128 v[180:183], v136 offset:1024
	ds_read_b128 v[184:187], v136 offset:2048
	ds_read_b128 v[188:191], v136 offset:3072
	ds_read_b128 v[196:199], v136 offset:4096
	ds_read_b128 v[200:203], v136 offset:5120
	ds_read_b128 v[204:207], v136 offset:6144
	ds_read_b128 v[208:211], v136 offset:7168
	s_add_u32 s96, s59, s96
	s_addc_u32 s97, s38, s97
	s_add_i32 m0, s43, 0xc000
	s_nop 0
	global_load_lds_dwordx4 v134, s[96:97]
	s_nop 0
	s_add_i32 m0, s43, 0xe000
	s_nop 0
	global_load_lds_dwordx4 v135, s[96:97]
	s_waitcnt vmcnt(8)
	s_waitcnt lgkmcnt(0)
	s_setprio 1
	s_barrier
	v_mfma_f32_16x16x32_bf16 v[70:73], v[142:145], v[176:179], v[70:73]
	v_mfma_f32_16x16x32_bf16 v[86:89], v[150:153], v[176:179], v[86:89]
	v_mfma_f32_16x16x32_bf16 v[74:77], v[142:145], v[184:187], v[74:77]
	v_mfma_f32_16x16x32_bf16 v[90:93], v[150:153], v[184:187], v[90:93]
	v_mfma_f32_16x16x32_bf16 v[78:81], v[142:145], v[196:199], v[78:81]
	v_mfma_f32_16x16x32_bf16 v[94:97], v[150:153], v[196:199], v[94:97]
	v_mfma_f32_16x16x32_bf16 v[82:85], v[142:145], v[204:207], v[82:85]
	v_mfma_f32_16x16x32_bf16 v[98:101], v[150:153], v[204:207], v[98:101]
	v_mfma_f32_16x16x32_bf16 v[70:73], v[146:149], v[180:183], v[70:73]
	v_mfma_f32_16x16x32_bf16 v[86:89], v[154:157], v[180:183], v[86:89]
	v_mfma_f32_16x16x32_bf16 v[74:77], v[146:149], v[188:191], v[74:77]
	v_mfma_f32_16x16x32_bf16 v[90:93], v[154:157], v[188:191], v[90:93]
	v_mfma_f32_16x16x32_bf16 v[78:81], v[146:149], v[200:203], v[78:81]
	v_mfma_f32_16x16x32_bf16 v[94:97], v[154:157], v[200:203], v[94:97]
	v_mfma_f32_16x16x32_bf16 v[82:85], v[146:149], v[208:211], v[82:85]
	v_mfma_f32_16x16x32_bf16 v[98:101], v[154:157], v[208:211], v[98:101]
	v_mfma_f32_16x16x32_bf16 v[102:105], v[158:161], v[176:179], v[102:105]
	v_mfma_f32_16x16x32_bf16 v[118:121], v[166:169], v[176:179], v[118:121]
	v_mfma_f32_16x16x32_bf16 v[106:109], v[158:161], v[184:187], v[106:109]
	v_mfma_f32_16x16x32_bf16 v[122:125], v[166:169], v[184:187], v[122:125]
	v_mfma_f32_16x16x32_bf16 v[110:113], v[158:161], v[196:199], v[110:113]
	v_mfma_f32_16x16x32_bf16 v[126:129], v[166:169], v[196:199], v[126:129]
	v_mfma_f32_16x16x32_bf16 v[114:117], v[158:161], v[204:207], v[114:117]
	v_mfma_f32_16x16x32_bf16 v[130:133], v[166:169], v[204:207], v[130:133]
	v_mfma_f32_16x16x32_bf16 v[102:105], v[162:165], v[180:183], v[102:105]
	v_mfma_f32_16x16x32_bf16 v[118:121], v[172:175], v[180:183], v[118:121]
	v_mfma_f32_16x16x32_bf16 v[106:109], v[162:165], v[188:191], v[106:109]
	v_mfma_f32_16x16x32_bf16 v[122:125], v[172:175], v[188:191], v[122:125]
	v_mfma_f32_16x16x32_bf16 v[110:113], v[162:165], v[200:203], v[110:113]
	v_mfma_f32_16x16x32_bf16 v[126:129], v[172:175], v[200:203], v[126:129]
	v_mfma_f32_16x16x32_bf16 v[114:117], v[162:165], v[208:211], v[114:117]
	v_mfma_f32_16x16x32_bf16 v[130:133], v[172:175], v[208:211], v[130:133]
	s_barrier
	s_setprio 0
	ds_read_b128 v[176:179], v136 offset:16384
	ds_read_b128 v[180:183], v136 offset:17408
	ds_read_b128 v[184:187], v136 offset:18432
	ds_read_b128 v[188:191], v136 offset:19456
	ds_read_b128 v[196:199], v136 offset:20480
	ds_read_b128 v[200:203], v136 offset:21504
	ds_read_b128 v[204:207], v136 offset:22528
	ds_read_b128 v[208:211], v136 offset:23552
	s_add_i32 m0, s43, 0x10000
	s_nop 0
	global_load_lds_dwordx4 v134, s[92:93]
	s_nop 0
	s_add_i32 m0, s43, 0x12000
	s_nop 0
	global_load_lds_dwordx4 v135, s[92:93]
	s_add_u32 s92, s92, s16
	s_addc_u32 s93, s93, 0
	s_add_i32 m0, s43, 0x14000
	s_nop 0
	global_load_lds_dwordx4 v134, s[92:93]
	s_nop 0
	s_add_i32 m0, s43, 0x16000
	s_nop 0
	global_load_lds_dwordx4 v135, s[92:93]
	s_nop 0
	s_add_i32 m0, s43, 0
	s_nop 0
	global_load_lds_dwordx4 v134, s[94:95]
	s_nop 0
	s_add_i32 m0, s43, 0x2000
	s_nop 0
	global_load_lds_dwordx4 v135, s[94:95]
	s_waitcnt vmcnt(8)
	s_waitcnt lgkmcnt(0)
	s_setprio 1
	s_barrier
	v_mfma_f32_16x16x32_bf16 v[4:7], v[142:145], v[176:179], v[6:9]
	v_mfma_f32_16x16x32_bf16 v[22:25], v[150:153], v[176:179], v[22:25]
	v_mfma_f32_16x16x32_bf16 v[8:11], v[142:145], v[184:187], v[10:13]
	v_mfma_f32_16x16x32_bf16 v[26:29], v[150:153], v[184:187], v[26:29]
	v_mfma_f32_16x16x32_bf16 v[14:17], v[142:145], v[196:199], v[14:17]
	v_mfma_f32_16x16x32_bf16 v[30:33], v[150:153], v[196:199], v[30:33]
	v_mfma_f32_16x16x32_bf16 v[18:21], v[142:145], v[204:207], v[18:21]
	v_mfma_f32_16x16x32_bf16 v[34:37], v[150:153], v[204:207], v[34:37]
	v_mfma_f32_16x16x32_bf16 v[4:7], v[146:149], v[180:183], v[4:7]
	v_mfma_f32_16x16x32_bf16 v[22:25], v[154:157], v[180:183], v[22:25]
	v_mfma_f32_16x16x32_bf16 v[10:13], v[146:149], v[188:191], v[8:11]
	v_mfma_f32_16x16x32_bf16 v[26:29], v[154:157], v[188:191], v[26:29]
	v_mfma_f32_16x16x32_bf16 v[14:17], v[146:149], v[200:203], v[14:17]
	v_mfma_f32_16x16x32_bf16 v[30:33], v[154:157], v[200:203], v[30:33]
	v_mfma_f32_16x16x32_bf16 v[18:21], v[146:149], v[208:211], v[18:21]
	v_mfma_f32_16x16x32_bf16 v[34:37], v[154:157], v[208:211], v[34:37]
	v_mfma_f32_16x16x32_bf16 v[38:41], v[158:161], v[176:179], v[38:41]
	v_mfma_f32_16x16x32_bf16 v[54:57], v[166:169], v[176:179], v[54:57]
	v_mfma_f32_16x16x32_bf16 v[42:45], v[158:161], v[184:187], v[42:45]
	v_mfma_f32_16x16x32_bf16 v[58:61], v[166:169], v[184:187], v[58:61]
	v_mfma_f32_16x16x32_bf16 v[46:49], v[158:161], v[196:199], v[46:49]
	v_mfma_f32_16x16x32_bf16 v[62:65], v[166:169], v[196:199], v[62:65]
	v_mfma_f32_16x16x32_bf16 v[50:53], v[158:161], v[204:207], v[50:53]
	v_mfma_f32_16x16x32_bf16 v[66:69], v[166:169], v[204:207], v[66:69]
	v_mfma_f32_16x16x32_bf16 v[38:41], v[162:165], v[180:183], v[38:41]
	v_mfma_f32_16x16x32_bf16 v[54:57], v[172:175], v[180:183], v[54:57]
	v_mfma_f32_16x16x32_bf16 v[42:45], v[162:165], v[188:191], v[42:45]
	v_mfma_f32_16x16x32_bf16 v[58:61], v[172:175], v[188:191], v[58:61]
	v_mfma_f32_16x16x32_bf16 v[46:49], v[162:165], v[200:203], v[46:49]
	v_mfma_f32_16x16x32_bf16 v[62:65], v[172:175], v[200:203], v[62:65]
	v_mfma_f32_16x16x32_bf16 v[50:53], v[162:165], v[208:211], v[50:53]
	v_mfma_f32_16x16x32_bf16 v[66:69], v[172:175], v[208:211], v[66:69]
	s_barrier
	s_setprio 0
	ds_read_b128 v[142:145], v139
	ds_read_b128 v[146:149], v139 offset:1024
	ds_read_b128 v[150:153], v139 offset:2048
	ds_read_b128 v[154:157], v139 offset:3072
	ds_read_b128 v[158:161], v140
	ds_read_b128 v[162:165], v140 offset:1024
	ds_read_b128 v[166:169], v140 offset:2048
	ds_read_b128 v[172:175], v140 offset:3072
	ds_read_b128 v[176:179], v136 offset:32768
	ds_read_b128 v[180:183], v136 offset:33792
	ds_read_b128 v[184:187], v136 offset:34816
	ds_read_b128 v[188:191], v136 offset:35840
	ds_read_b128 v[196:199], v136 offset:36864
	ds_read_b128 v[200:203], v136 offset:37888
	ds_read_b128 v[204:207], v136 offset:38912
	ds_read_b128 v[208:211], v136 offset:39936
	s_add_u32 s92, s94, s16
	s_addc_u32 s93, s95, 0
	s_add_i32 m0, s43, 0x4000
	s_nop 0
	global_load_lds_dwordx4 v134, s[92:93]
	s_nop 0
	s_add_i32 m0, s43, 0x6000
	s_nop 0
	global_load_lds_dwordx4 v135, s[92:93]
	s_waitcnt vmcnt(8)
	s_waitcnt lgkmcnt(0)
	s_setprio 1
	s_barrier
	v_mfma_f32_16x16x32_bf16 v[70:73], v[142:145], v[176:179], v[70:73]
	v_mfma_f32_16x16x32_bf16 v[86:89], v[150:153], v[176:179], v[86:89]
	v_mfma_f32_16x16x32_bf16 v[74:77], v[142:145], v[184:187], v[74:77]
	v_mfma_f32_16x16x32_bf16 v[90:93], v[150:153], v[184:187], v[90:93]
	v_mfma_f32_16x16x32_bf16 v[78:81], v[142:145], v[196:199], v[78:81]
	v_mfma_f32_16x16x32_bf16 v[94:97], v[150:153], v[196:199], v[94:97]
	v_mfma_f32_16x16x32_bf16 v[82:85], v[142:145], v[204:207], v[82:85]
	v_mfma_f32_16x16x32_bf16 v[98:101], v[150:153], v[204:207], v[98:101]
	v_mfma_f32_16x16x32_bf16 v[70:73], v[146:149], v[180:183], v[70:73]
	v_mfma_f32_16x16x32_bf16 v[86:89], v[154:157], v[180:183], v[86:89]
	v_mfma_f32_16x16x32_bf16 v[74:77], v[146:149], v[188:191], v[74:77]
	v_mfma_f32_16x16x32_bf16 v[90:93], v[154:157], v[188:191], v[90:93]
	v_mfma_f32_16x16x32_bf16 v[78:81], v[146:149], v[200:203], v[78:81]
	v_mfma_f32_16x16x32_bf16 v[94:97], v[154:157], v[200:203], v[94:97]
	v_mfma_f32_16x16x32_bf16 v[82:85], v[146:149], v[208:211], v[82:85]
	v_mfma_f32_16x16x32_bf16 v[98:101], v[154:157], v[208:211], v[98:101]
	v_mfma_f32_16x16x32_bf16 v[102:105], v[158:161], v[176:179], v[102:105]
	v_mfma_f32_16x16x32_bf16 v[118:121], v[166:169], v[176:179], v[118:121]
	v_mfma_f32_16x16x32_bf16 v[106:109], v[158:161], v[184:187], v[106:109]
	v_mfma_f32_16x16x32_bf16 v[122:125], v[166:169], v[184:187], v[122:125]
	v_mfma_f32_16x16x32_bf16 v[110:113], v[158:161], v[196:199], v[110:113]
	v_mfma_f32_16x16x32_bf16 v[126:129], v[166:169], v[196:199], v[126:129]
	v_mfma_f32_16x16x32_bf16 v[114:117], v[158:161], v[204:207], v[114:117]
	v_mfma_f32_16x16x32_bf16 v[130:133], v[166:169], v[204:207], v[130:133]
	v_mfma_f32_16x16x32_bf16 v[102:105], v[162:165], v[180:183], v[102:105]
	v_mfma_f32_16x16x32_bf16 v[118:121], v[172:175], v[180:183], v[118:121]
	v_mfma_f32_16x16x32_bf16 v[106:109], v[162:165], v[188:191], v[106:109]
	v_mfma_f32_16x16x32_bf16 v[122:125], v[172:175], v[188:191], v[122:125]
	v_mfma_f32_16x16x32_bf16 v[110:113], v[162:165], v[200:203], v[110:113]
	v_mfma_f32_16x16x32_bf16 v[126:129], v[172:175], v[200:203], v[126:129]
	v_mfma_f32_16x16x32_bf16 v[114:117], v[162:165], v[208:211], v[114:117]
	v_mfma_f32_16x16x32_bf16 v[130:133], v[172:175], v[208:211], v[130:133]
	s_barrier
	s_setprio 0
	ds_read_b128 v[176:179], v136 offset:49152
	ds_read_b128 v[180:183], v136 offset:50176
	ds_read_b128 v[184:187], v136 offset:51200
	ds_read_b128 v[188:191], v136 offset:52224
	ds_read_b128 v[196:199], v136 offset:53248
	ds_read_b128 v[200:203], v136 offset:54272
	ds_read_b128 v[204:207], v136 offset:55296
	ds_read_b128 v[208:211], v136 offset:56320
	s_add_i32 m0, s43, 0x18000
	s_nop 0
	global_load_lds_dwordx4 v134, s[12:13]
	s_nop 0
	s_add_i32 m0, s43, 0x1a000
	s_nop 0
	global_load_lds_dwordx4 v135, s[12:13]
	s_add_u32 s12, s12, s16
	s_addc_u32 s13, s13, 0
	s_add_i32 m0, s43, 0x1c000
	s_nop 0
	global_load_lds_dwordx4 v134, s[12:13]
	s_nop 0
	s_add_i32 m0, s43, 0x1e000
	s_nop 0
	global_load_lds_dwordx4 v135, s[12:13]
	s_nop 0
	s_add_i32 m0, s43, 0x8000
	s_nop 0
	global_load_lds_dwordx4 v134, s[2:3]
	s_nop 0
	s_add_i32 m0, s43, 0xa000
	s_nop 0
	global_load_lds_dwordx4 v135, s[2:3]
	s_waitcnt vmcnt(8)
	s_waitcnt lgkmcnt(0)
	s_setprio 1
	s_barrier
	v_mfma_f32_16x16x32_bf16 v[4:7], v[142:145], v[176:179], v[4:7]
	v_mfma_f32_16x16x32_bf16 v[22:25], v[150:153], v[176:179], v[22:25]
	v_mfma_f32_16x16x32_bf16 v[10:13], v[142:145], v[184:187], v[10:13]
	v_mfma_f32_16x16x32_bf16 v[26:29], v[150:153], v[184:187], v[26:29]
	v_mfma_f32_16x16x32_bf16 v[14:17], v[142:145], v[196:199], v[14:17]
	v_mfma_f32_16x16x32_bf16 v[30:33], v[150:153], v[196:199], v[30:33]
	v_mfma_f32_16x16x32_bf16 v[18:21], v[142:145], v[204:207], v[18:21]
	v_mfma_f32_16x16x32_bf16 v[34:37], v[150:153], v[204:207], v[34:37]
	v_mfma_f32_16x16x32_bf16 v[6:9], v[146:149], v[180:183], v[4:7]
	v_mfma_f32_16x16x32_bf16 v[22:25], v[154:157], v[180:183], v[22:25]
	v_mfma_f32_16x16x32_bf16 v[10:13], v[146:149], v[188:191], v[10:13]
	v_mfma_f32_16x16x32_bf16 v[26:29], v[154:157], v[188:191], v[26:29]
	v_mfma_f32_16x16x32_bf16 v[14:17], v[146:149], v[200:203], v[14:17]
	v_mfma_f32_16x16x32_bf16 v[30:33], v[154:157], v[200:203], v[30:33]
	v_mfma_f32_16x16x32_bf16 v[18:21], v[146:149], v[208:211], v[18:21]
	v_mfma_f32_16x16x32_bf16 v[34:37], v[154:157], v[208:211], v[34:37]
	v_mfma_f32_16x16x32_bf16 v[38:41], v[158:161], v[176:179], v[38:41]
	v_mfma_f32_16x16x32_bf16 v[54:57], v[166:169], v[176:179], v[54:57]
	v_mfma_f32_16x16x32_bf16 v[42:45], v[158:161], v[184:187], v[42:45]
	v_mfma_f32_16x16x32_bf16 v[58:61], v[166:169], v[184:187], v[58:61]
	v_mfma_f32_16x16x32_bf16 v[46:49], v[158:161], v[196:199], v[46:49]
	v_mfma_f32_16x16x32_bf16 v[62:65], v[166:169], v[196:199], v[62:65]
	v_mfma_f32_16x16x32_bf16 v[50:53], v[158:161], v[204:207], v[50:53]
	v_mfma_f32_16x16x32_bf16 v[66:69], v[166:169], v[204:207], v[66:69]
	v_mfma_f32_16x16x32_bf16 v[38:41], v[162:165], v[180:183], v[38:41]
	v_mfma_f32_16x16x32_bf16 v[54:57], v[172:175], v[180:183], v[54:57]
	v_mfma_f32_16x16x32_bf16 v[42:45], v[162:165], v[188:191], v[42:45]
	v_mfma_f32_16x16x32_bf16 v[58:61], v[172:175], v[188:191], v[58:61]
	v_mfma_f32_16x16x32_bf16 v[46:49], v[162:165], v[200:203], v[46:49]
	v_mfma_f32_16x16x32_bf16 v[62:65], v[172:175], v[200:203], v[62:65]
	v_mfma_f32_16x16x32_bf16 v[50:53], v[162:165], v[208:211], v[50:53]
	v_mfma_f32_16x16x32_bf16 v[66:69], v[172:175], v[208:211], v[66:69]
	s_barrier
	s_setprio 0
	s_cmp_ge_u32 s90, s55
	s_cbranch_scc1 .LBB0_848

.LBB0_1071:
	s_add_i32 s16, s38, 1
	s_add_i32 s3, s16, s35
	s_mul_i32 s3, s3, s23
	s_add_i32 s3, s3, s22
	s_add_i32 s12, s18, s3
	s_cmp_lt_i32 s12, s2
	s_cselect_b64 s[78:79], -1, 0
	s_cmp_ge_i32 s12, s2
	s_cselect_b64 s[74:75], -1, 0
	s_lshr_b32 s2, s2, 1
	s_cmp_lt_i32 s12, s2
	s_cselect_b32 s2, 0, s2
	s_cselect_b32 s13, 0, 4
	s_sub_i32 s2, s12, s2
	s_and_b32 s3, s3, 3
	s_ashr_i32 s37, s2, 2
	s_or_b32 s2, s3, s13
	s_or_b32 s53, s2, s28
	s_and_b64 s[2:3], s[78:79], exec
	s_cselect_b32 s82, s53, s7
	s_cselect_b32 s2, s37, s6
	s_ashr_i32 s83, s82, 31
	s_lshl_b64 s[6:7], s[82:83], 19
	s_add_u32 s76, s51, s6
	s_addc_u32 s77, s97, s7
	s_ashr_i32 s3, s2, 31
	s_lshl_b64 s[2:3], s[2:3], 19
	s_add_u32 s80, s56, s2
	s_addc_u32 s81, s96, s3
	s_add_u32 s12, s62, 0x100
	s_addc_u32 s13, s63, 0
	v_add_u32_e32 v134, 0x10000, v151
	v_add_u32_e32 v135, 0x14000, v151
	s_add_u32 s2, s62, 0x180
	ds_read_b128 v[4:7], v134
	ds_read_b128 v[8:11], v134 offset:1024
	ds_read_b128 v[12:15], v134 offset:2048
	ds_read_b128 v[16:19], v134 offset:3072
	ds_read_b128 v[20:23], v135
	ds_read_b128 v[24:27], v135 offset:1024
	ds_read_b128 v[28:31], v135 offset:2048
	ds_read_b128 v[32:35], v135 offset:3072
	s_addc_u32 s3, s63, 0
	s_and_b64 s[6:7], s[78:79], exec
	s_cselect_b32 s33, s77, s63
	s_cselect_b32 s39, s76, s62
	s_add_u32 s6, s64, 0x100
	s_addc_u32 s7, s65, 0
	s_and_b64 s[26:27], s[78:79], exec
	s_mov_b32 s29, 2
	s_cselect_b32 s54, s81, s65
	s_cselect_b32 s47, s80, s64
	ds_read_b128 v[36:39], v152
	ds_read_b128 v[40:43], v152 offset:1024
	ds_read_b128 v[44:47], v152 offset:2048
	ds_read_b128 v[48:51], v152 offset:3072
	ds_read_b128 v[52:55], v152 offset:4096
	ds_read_b128 v[56:59], v152 offset:5120
	ds_read_b128 v[60:63], v152 offset:6144
	ds_read_b128 v[64:67], v152 offset:7168
	s_add_u32 s26, s62, 0x40080
	s_addc_u32 s27, s63, 0
	s_add_i32 m0, s69, 0xc000
	s_nop 0
	global_load_lds_dwordx4 v147, s[26:27]
	s_nop 0
	s_add_i32 m0, s69, 0xe000
	s_nop 0
	global_load_lds_dwordx4 v148, s[26:27]
	s_waitcnt vmcnt(8)
	s_waitcnt lgkmcnt(0)
	s_setprio 1
	s_barrier
	v_mfma_f32_16x16x32_bf16 v[92:95], v[4:7], v[60:63], 0
	v_mfma_f32_16x16x32_bf16 v[68:71], v[4:7], v[36:39], 0
	v_mfma_f32_16x16x32_bf16 v[72:75], v[12:15], v[36:39], 0
	v_mfma_f32_16x16x32_bf16 v[76:79], v[4:7], v[44:47], 0
	v_mfma_f32_16x16x32_bf16 v[80:83], v[12:15], v[44:47], 0
	v_mfma_f32_16x16x32_bf16 v[84:87], v[4:7], v[52:55], 0
	v_mfma_f32_16x16x32_bf16 v[88:91], v[12:15], v[52:55], 0
	v_mfma_f32_16x16x32_bf16 v[96:99], v[8:11], v[64:67], v[92:95]
	v_mfma_f32_16x16x32_bf16 v[92:95], v[12:15], v[60:63], 0
	v_mfma_f32_16x16x32_bf16 v[68:71], v[8:11], v[40:43], v[68:71]
	v_mfma_f32_16x16x32_bf16 v[72:75], v[16:19], v[40:43], v[72:75]
	v_mfma_f32_16x16x32_bf16 v[76:79], v[8:11], v[48:51], v[76:79]
	v_mfma_f32_16x16x32_bf16 v[80:83], v[16:19], v[48:51], v[80:83]
	v_mfma_f32_16x16x32_bf16 v[84:87], v[8:11], v[56:59], v[84:87]
	v_mfma_f32_16x16x32_bf16 v[88:91], v[16:19], v[56:59], v[88:91]
	v_mfma_f32_16x16x32_bf16 v[104:107], v[16:19], v[64:67], v[92:95]
	v_mfma_f32_16x16x32_bf16 v[92:95], v[20:23], v[36:39], 0
	v_mfma_f32_16x16x32_bf16 v[36:39], v[28:31], v[36:39], 0
	v_mfma_f32_16x16x32_bf16 v[112:115], v[24:27], v[40:43], v[92:95]
	v_mfma_f32_16x16x32_bf16 v[36:39], v[32:35], v[40:43], v[36:39]
	v_mfma_f32_16x16x32_bf16 v[40:43], v[20:23], v[44:47], 0
	v_mfma_f32_16x16x32_bf16 v[44:47], v[28:31], v[44:47], 0
	v_mfma_f32_16x16x32_bf16 v[40:43], v[24:27], v[48:51], v[40:43]
	v_mfma_f32_16x16x32_bf16 v[44:47], v[32:35], v[48:51], v[44:47]
	v_mfma_f32_16x16x32_bf16 v[48:51], v[20:23], v[52:55], 0
	v_mfma_f32_16x16x32_bf16 v[52:55], v[28:31], v[52:55], 0
	v_mfma_f32_16x16x32_bf16 v[48:51], v[24:27], v[56:59], v[48:51]
	v_mfma_f32_16x16x32_bf16 v[52:55], v[32:35], v[56:59], v[52:55]
	v_mfma_f32_16x16x32_bf16 v[56:59], v[20:23], v[60:63], 0
	v_mfma_f32_16x16x32_bf16 v[60:63], v[28:31], v[60:63], 0
	v_mfma_f32_16x16x32_bf16 v[56:59], v[24:27], v[64:67], v[56:59]
	v_mfma_f32_16x16x32_bf16 v[60:63], v[32:35], v[64:67], v[60:63]
	s_barrier
	s_setprio 0
	ds_read_b128 v[64:67], v152 offset:16384
	ds_read_b128 v[92:95], v152 offset:17408
	ds_read_b128 v[100:103], v152 offset:18432
	ds_read_b128 v[108:111], v152 offset:19456
	ds_read_b128 v[116:119], v152 offset:20480
	ds_read_b128 v[120:123], v152 offset:21504
	ds_read_b128 v[124:127], v152 offset:22528
	ds_read_b128 v[128:131], v152 offset:23552
	s_add_i32 m0, s69, 0x10000
	s_nop 0
	global_load_lds_dwordx4 v1, s[6:7]
	s_nop 0
	s_add_i32 m0, s69, 0x12000
	s_nop 0
	global_load_lds_dwordx4 v146, s[6:7]
	s_add_u32 s6, s64, 0x40100
	s_addc_u32 s7, s65, 0
	s_add_i32 m0, s69, 0x14000
	s_nop 0
	global_load_lds_dwordx4 v1, s[6:7]
	s_nop 0
	s_add_i32 m0, s69, 0x16000
	s_nop 0
	global_load_lds_dwordx4 v146, s[6:7]
	s_nop 0
	s_add_i32 m0, s69, 0
	s_nop 0
	global_load_lds_dwordx4 v147, s[12:13]
	s_nop 0
	s_add_i32 m0, s69, 0x2000
	s_nop 0
	global_load_lds_dwordx4 v148, s[12:13]
	s_waitcnt vmcnt(8)
	s_waitcnt lgkmcnt(0)
	s_setprio 1
	s_barrier
	v_mfma_f32_16x16x32_bf16 v[136:139], v[4:7], v[64:67], 0
	v_mfma_f32_16x16x32_bf16 v[154:157], v[4:7], v[100:103], 0
	v_mfma_f32_16x16x32_bf16 v[162:165], v[4:7], v[116:119], 0
	v_mfma_f32_16x16x32_bf16 v[4:7], v[4:7], v[124:127], 0
	v_mfma_f32_16x16x32_bf16 v[138:141], v[8:11], v[92:95], v[136:139]
	v_mfma_f32_16x16x32_bf16 v[154:157], v[8:11], v[108:111], v[154:157]
	v_mfma_f32_16x16x32_bf16 v[162:165], v[8:11], v[120:123], v[162:165]
	v_mfma_f32_16x16x32_bf16 v[4:7], v[8:11], v[128:131], v[4:7]
	v_mfma_f32_16x16x32_bf16 v[8:11], v[12:15], v[124:127], 0
	v_mfma_f32_16x16x32_bf16 v[142:145], v[12:15], v[64:67], 0
	v_mfma_f32_16x16x32_bf16 v[158:161], v[12:15], v[100:103], 0
	v_mfma_f32_16x16x32_bf16 v[166:169], v[12:15], v[116:119], 0
	v_mfma_f32_16x16x32_bf16 v[8:11], v[16:19], v[128:131], v[8:11]
	v_mfma_f32_16x16x32_bf16 v[142:145], v[16:19], v[92:95], v[142:145]
	v_mfma_f32_16x16x32_bf16 v[158:161], v[16:19], v[108:111], v[158:161]
	v_mfma_f32_16x16x32_bf16 v[166:169], v[16:19], v[120:123], v[166:169]
	v_mfma_f32_16x16x32_bf16 v[12:15], v[20:23], v[64:67], 0
	v_mfma_f32_16x16x32_bf16 v[16:19], v[24:27], v[92:95], v[12:15]
	v_mfma_f32_16x16x32_bf16 v[12:15], v[28:31], v[64:67], 0
	v_mfma_f32_16x16x32_bf16 v[172:175], v[32:35], v[92:95], v[12:15]
	v_mfma_f32_16x16x32_bf16 v[12:15], v[20:23], v[100:103], 0
	v_mfma_f32_16x16x32_bf16 v[176:179], v[24:27], v[108:111], v[12:15]
	v_mfma_f32_16x16x32_bf16 v[12:15], v[28:31], v[100:103], 0
	v_mfma_f32_16x16x32_bf16 v[180:183], v[32:35], v[108:111], v[12:15]
	v_mfma_f32_16x16x32_bf16 v[12:15], v[20:23], v[116:119], 0
	v_mfma_f32_16x16x32_bf16 v[184:187], v[24:27], v[120:123], v[12:15]
	v_mfma_f32_16x16x32_bf16 v[12:15], v[28:31], v[116:119], 0
	v_mfma_f32_16x16x32_bf16 v[204:207], v[32:35], v[120:123], v[12:15]
	v_mfma_f32_16x16x32_bf16 v[12:15], v[20:23], v[124:127], 0
	v_mfma_f32_16x16x32_bf16 v[208:211], v[24:27], v[128:131], v[12:15]
	v_mfma_f32_16x16x32_bf16 v[12:15], v[28:31], v[124:127], 0
	v_mfma_f32_16x16x32_bf16 v[212:215], v[32:35], v[128:131], v[12:15]
	s_barrier
	s_setprio 0
	v_add_u32_e32 v136, 0x18000, v151
	v_add_u32_e32 v137, 0x1c000, v151
	s_nop 2
	ds_read_b128 v[12:15], v136
	ds_read_b128 v[24:27], v136 offset:1024
	ds_read_b128 v[32:35], v136 offset:2048
	ds_read_b128 v[216:219], v136 offset:3072
	ds_read_b128 v[220:223], v137
	ds_read_b128 v[224:227], v137 offset:1024
	ds_read_b128 v[228:231], v137 offset:2048
	ds_read_b128 v[232:235], v137 offset:3072
	ds_read_b128 v[20:23], v152 offset:32768
	ds_read_b128 v[28:31], v152 offset:33792
	ds_read_b128 v[236:239], v152 offset:34816
	ds_read_b128 v[240:243], v152 offset:35840
	ds_read_b128 v[244:247], v152 offset:36864
	ds_read_b128 v[248:251], v152 offset:37888
	ds_read_b128 v[200:203], v152 offset:38912
	ds_read_b128 v[196:199], v152 offset:39936
	s_add_u32 s6, s62, 0x40100
	s_addc_u32 s7, s63, 0
	s_add_i32 m0, s69, 0x4000
	s_nop 0
	global_load_lds_dwordx4 v147, s[6:7]
	s_nop 0
	s_add_i32 m0, s69, 0x6000
	s_nop 0
	global_load_lds_dwordx4 v148, s[6:7]
	s_waitcnt vmcnt(8)
	s_waitcnt lgkmcnt(0)
	s_setprio 1
	s_barrier
	v_mfma_f32_16x16x32_bf16 v[64:67], v[12:15], v[20:23], v[68:71]
	v_mfma_f32_16x16x32_bf16 v[124:127], v[24:27], v[28:31], v[64:67]
	v_mfma_f32_16x16x32_bf16 v[64:67], v[32:35], v[20:23], v[72:75]
	v_mfma_f32_16x16x32_bf16 v[116:119], v[216:219], v[28:31], v[64:67]
	v_mfma_f32_16x16x32_bf16 v[64:67], v[12:15], v[236:239], v[76:79]
	v_mfma_f32_16x16x32_bf16 v[108:111], v[24:27], v[240:243], v[64:67]
	v_mfma_f32_16x16x32_bf16 v[64:67], v[32:35], v[236:239], v[80:83]
	v_mfma_f32_16x16x32_bf16 v[100:103], v[216:219], v[240:243], v[64:67]
	v_mfma_f32_16x16x32_bf16 v[64:67], v[12:15], v[244:247], v[84:87]
	v_mfma_f32_16x16x32_bf16 v[92:95], v[24:27], v[248:251], v[64:67]
	v_mfma_f32_16x16x32_bf16 v[64:67], v[32:35], v[244:247], v[88:91]
	v_mfma_f32_16x16x32_bf16 v[84:87], v[216:219], v[248:251], v[64:67]
	v_mfma_f32_16x16x32_bf16 v[64:67], v[12:15], v[200:203], v[96:99]
	v_mfma_f32_16x16x32_bf16 v[76:79], v[24:27], v[196:199], v[64:67]
	v_mfma_f32_16x16x32_bf16 v[64:67], v[32:35], v[200:203], v[104:107]
	v_mfma_f32_16x16x32_bf16 v[64:67], v[216:219], v[196:199], v[64:67]
	v_mfma_f32_16x16x32_bf16 v[68:71], v[220:223], v[20:23], v[112:115]
	v_mfma_f32_16x16x32_bf16 v[20:23], v[228:231], v[20:23], v[36:39]
	v_mfma_f32_16x16x32_bf16 v[120:123], v[232:235], v[28:31], v[20:23]
	v_mfma_f32_16x16x32_bf16 v[20:23], v[220:223], v[236:239], v[40:43]
	v_mfma_f32_16x16x32_bf16 v[112:115], v[224:227], v[240:243], v[20:23]
	v_mfma_f32_16x16x32_bf16 v[20:23], v[228:231], v[236:239], v[44:47]
	v_mfma_f32_16x16x32_bf16 v[104:107], v[232:235], v[240:243], v[20:23]
	v_mfma_f32_16x16x32_bf16 v[20:23], v[220:223], v[244:247], v[48:51]
	v_mfma_f32_16x16x32_bf16 v[96:99], v[224:227], v[248:251], v[20:23]
	v_mfma_f32_16x16x32_bf16 v[20:23], v[228:231], v[244:247], v[52:55]
	v_mfma_f32_16x16x32_bf16 v[88:91], v[232:235], v[248:251], v[20:23]
	v_mfma_f32_16x16x32_bf16 v[20:23], v[220:223], v[200:203], v[56:59]
	v_mfma_f32_16x16x32_bf16 v[80:83], v[224:227], v[196:199], v[20:23]
	v_mfma_f32_16x16x32_bf16 v[20:23], v[228:231], v[200:203], v[60:63]
	v_mfma_f32_16x16x32_bf16 v[128:131], v[224:227], v[28:31], v[68:71]
	v_mfma_f32_16x16x32_bf16 v[72:75], v[232:235], v[196:199], v[20:23]
	s_barrier
	s_setprio 0
	s_add_u32 s6, s64, 0x180
	ds_read_b128 v[40:43], v152 offset:49152
	ds_read_b128 v[48:51], v152 offset:50176
	ds_read_b128 v[196:199], v152 offset:51200
	ds_read_b128 v[200:203], v152 offset:52224
	ds_read_b128 v[236:239], v152 offset:53248
	ds_read_b128 v[240:243], v152 offset:54272
	ds_read_b128 v[244:247], v152 offset:55296
	ds_read_b128 v[248:251], v152 offset:56320
	s_addc_u32 s7, s65, 0
	s_add_i32 m0, s69, 0x18000
	s_nop 0
	global_load_lds_dwordx4 v1, s[6:7]
	s_nop 0
	s_add_i32 m0, s69, 0x1a000
	s_nop 0
	global_load_lds_dwordx4 v146, s[6:7]
	s_add_u32 s6, s64, 0x40180
	s_addc_u32 s7, s65, 0
	s_add_i32 m0, s69, 0x1c000
	s_nop 0
	global_load_lds_dwordx4 v1, s[6:7]
	s_nop 0
	s_add_i32 m0, s69, 0x1e000
	s_nop 0
	global_load_lds_dwordx4 v146, s[6:7]
	s_nop 0
	s_add_i32 m0, s69, 0x8000
	s_nop 0
	global_load_lds_dwordx4 v147, s[2:3]
	s_nop 0
	s_add_i32 m0, s69, 0xa000
	s_nop 0
	global_load_lds_dwordx4 v148, s[2:3]
	s_waitcnt vmcnt(8)
	s_waitcnt lgkmcnt(0)
	s_setprio 1
	s_barrier
	v_mfma_f32_16x16x32_bf16 v[20:23], v[12:15], v[40:43], v[138:141]
	v_mfma_f32_16x16x32_bf16 v[60:63], v[24:27], v[48:51], v[20:23]
	v_mfma_f32_16x16x32_bf16 v[20:23], v[32:35], v[40:43], v[142:145]
	v_mfma_f32_16x16x32_bf16 v[52:55], v[216:219], v[48:51], v[20:23]
	v_mfma_f32_16x16x32_bf16 v[20:23], v[12:15], v[196:199], v[154:157]
	v_mfma_f32_16x16x32_bf16 v[44:47], v[24:27], v[200:203], v[20:23]
	v_mfma_f32_16x16x32_bf16 v[20:23], v[32:35], v[196:199], v[158:161]
	v_mfma_f32_16x16x32_bf16 v[36:39], v[216:219], v[200:203], v[20:23]
	v_mfma_f32_16x16x32_bf16 v[20:23], v[12:15], v[236:239], v[162:165]
	v_mfma_f32_16x16x32_bf16 v[4:7], v[12:15], v[244:247], v[4:7]
	v_mfma_f32_16x16x32_bf16 v[28:31], v[24:27], v[240:243], v[20:23]
	v_mfma_f32_16x16x32_bf16 v[20:23], v[32:35], v[236:239], v[166:169]
	v_mfma_f32_16x16x32_bf16 v[12:15], v[24:27], v[248:251], v[4:7]
	v_mfma_f32_16x16x32_bf16 v[4:7], v[32:35], v[244:247], v[8:11]
	v_mfma_f32_16x16x32_bf16 v[20:23], v[216:219], v[240:243], v[20:23]
	v_mfma_f32_16x16x32_bf16 v[4:7], v[216:219], v[248:251], v[4:7]
	v_mfma_f32_16x16x32_bf16 v[8:11], v[220:223], v[40:43], v[16:19]
	v_mfma_f32_16x16x32_bf16 v[68:71], v[224:227], v[48:51], v[8:11]
	v_mfma_f32_16x16x32_bf16 v[8:11], v[228:231], v[40:43], v[172:175]
	v_mfma_f32_16x16x32_bf16 v[56:59], v[232:235], v[48:51], v[8:11]
	v_mfma_f32_16x16x32_bf16 v[8:11], v[220:223], v[196:199], v[176:179]
	v_mfma_f32_16x16x32_bf16 v[48:51], v[224:227], v[200:203], v[8:11]
	v_mfma_f32_16x16x32_bf16 v[8:11], v[228:231], v[196:199], v[180:183]
	v_mfma_f32_16x16x32_bf16 v[40:43], v[232:235], v[200:203], v[8:11]
	v_mfma_f32_16x16x32_bf16 v[8:11], v[220:223], v[236:239], v[184:187]
	v_mfma_f32_16x16x32_bf16 v[32:35], v[224:227], v[240:243], v[8:11]
	v_mfma_f32_16x16x32_bf16 v[8:11], v[228:231], v[236:239], v[204:207]
	v_mfma_f32_16x16x32_bf16 v[24:27], v[232:235], v[240:243], v[8:11]
	v_mfma_f32_16x16x32_bf16 v[8:11], v[220:223], v[244:247], v[208:211]
	v_mfma_f32_16x16x32_bf16 v[16:19], v[224:227], v[248:251], v[8:11]
	v_mfma_f32_16x16x32_bf16 v[8:11], v[228:231], v[244:247], v[212:215]
	v_mfma_f32_16x16x32_bf16 v[8:11], v[232:235], v[248:251], v[8:11]
	s_barrier
	s_setprio 0
	s_add_i32 s2, s82, 1
	s_lshl_b32 s58, s82, 6
	s_and_b32 s3, s2, 31
	s_lshl_b32 s2, s2, 6
	s_add_i32 s59, s58, 0x9000
	s_add_i32 s52, s58, 0x8000
	s_add_i32 s40, s58, 0x7000
	s_addk_i32 s2, 0x6000
	s_cmp_eq_u32 s3, 0
	s_cselect_b32 s41, 0, 32
	s_cselect_b32 s50, 0, s2
	s_add_i32 s18, s58, 0x6000
	s_add_i32 s26, s58, 0x5000
	s_and_b32 s2, s82, 31
	s_add_i32 s3, s58, 0x4fc0
	s_cmp_eq_u32 s2, 0
	s_cselect_b32 s27, 0, 0x48
	s_cselect_b32 s6, 0, s3
	s_add_i32 s7, s58, 0x4000
	s_addk_i32 s58, 0x3000
	s_lshl_b64 s[2:3], s[82:83], 14
	s_add_u32 s84, s20, s2
	s_addc_u32 s85, s36, s3
	s_lshl_b32 s2, s82, 8
	s_and_b32 s2, s2, 0x400
	s_add_i32 s83, s2, 0
	s_add_i32 s83, s83, 0x24400

.LBB0_1192:
	s_lshl_b32 s12, s29, 7
	s_add_u32 s90, s62, s12
	s_addc_u32 s91, s63, 0
	s_add_u32 s13, s90, 0x100
	ds_read_b128 v[138:141], v134
	ds_read_b128 v[142:145], v134 offset:1024
	ds_read_b128 v[154:157], v134 offset:2048
	ds_read_b128 v[158:161], v134 offset:3072
	ds_read_b128 v[162:165], v135
	ds_read_b128 v[166:169], v135 offset:1024
	ds_read_b128 v[172:175], v135 offset:2048
	ds_read_b128 v[176:179], v135 offset:3072
	s_addc_u32 s88, s91, 0
	s_and_b64 s[2:3], s[86:87], exec
	s_cselect_b32 s89, s33, s88
	s_cselect_b32 s88, s39, s13
	s_add_u32 s2, s64, s12
	s_addc_u32 s3, s65, 0
	s_add_u32 s12, s2, 0x100
	s_addc_u32 s13, s3, 0
	s_and_b64 s[2:3], s[86:87], exec
	s_cselect_b32 s3, s54, s13
	s_cselect_b32 s2, s47, s12
	s_add_u32 s12, s88, 0x80
	s_addc_u32 s13, s89, 0
	s_add_u32 s86, s2, 0x80
	s_addc_u32 s87, s3, 0
	ds_read_b128 v[180:183], v152
	ds_read_b128 v[184:187], v152 offset:1024
	ds_read_b128 v[196:199], v152 offset:2048
	ds_read_b128 v[200:203], v152 offset:3072
	ds_read_b128 v[204:207], v152 offset:4096
	ds_read_b128 v[208:211], v152 offset:5120
	ds_read_b128 v[212:215], v152 offset:6144
	ds_read_b128 v[216:219], v152 offset:7168
	s_add_u32 s90, s90, 0x40080
	s_addc_u32 s91, s91, 0
	s_add_i32 m0, s69, 0xc000
	s_nop 0
	global_load_lds_dwordx4 v147, s[90:91]
	s_nop 0
	s_add_i32 m0, s69, 0xe000
	s_nop 0
	global_load_lds_dwordx4 v148, s[90:91]
	s_waitcnt vmcnt(8)
	s_waitcnt lgkmcnt(0)
	s_setprio 1
	s_barrier
	v_mfma_f32_16x16x32_bf16 v[124:127], v[138:141], v[180:183], v[124:127]
	v_mfma_f32_16x16x32_bf16 v[116:119], v[154:157], v[180:183], v[116:119]
	v_mfma_f32_16x16x32_bf16 v[108:111], v[138:141], v[196:199], v[108:111]
	v_mfma_f32_16x16x32_bf16 v[100:103], v[154:157], v[196:199], v[100:103]
	v_mfma_f32_16x16x32_bf16 v[92:95], v[138:141], v[204:207], v[92:95]
	v_mfma_f32_16x16x32_bf16 v[84:87], v[154:157], v[204:207], v[84:87]
	v_mfma_f32_16x16x32_bf16 v[76:79], v[138:141], v[212:215], v[76:79]
	v_mfma_f32_16x16x32_bf16 v[64:67], v[154:157], v[212:215], v[64:67]
	v_mfma_f32_16x16x32_bf16 v[124:127], v[142:145], v[184:187], v[124:127]
	v_mfma_f32_16x16x32_bf16 v[116:119], v[158:161], v[184:187], v[116:119]
	v_mfma_f32_16x16x32_bf16 v[108:111], v[142:145], v[200:203], v[108:111]
	v_mfma_f32_16x16x32_bf16 v[100:103], v[158:161], v[200:203], v[100:103]
	v_mfma_f32_16x16x32_bf16 v[92:95], v[142:145], v[208:211], v[92:95]
	v_mfma_f32_16x16x32_bf16 v[84:87], v[158:161], v[208:211], v[84:87]
	v_mfma_f32_16x16x32_bf16 v[76:79], v[142:145], v[216:219], v[76:79]
	v_mfma_f32_16x16x32_bf16 v[64:67], v[158:161], v[216:219], v[64:67]
	v_mfma_f32_16x16x32_bf16 v[128:131], v[162:165], v[180:183], v[128:131]
	v_mfma_f32_16x16x32_bf16 v[120:123], v[172:175], v[180:183], v[120:123]
	v_mfma_f32_16x16x32_bf16 v[112:115], v[162:165], v[196:199], v[112:115]
	v_mfma_f32_16x16x32_bf16 v[104:107], v[172:175], v[196:199], v[104:107]
	v_mfma_f32_16x16x32_bf16 v[96:99], v[162:165], v[204:207], v[96:99]
	v_mfma_f32_16x16x32_bf16 v[88:91], v[172:175], v[204:207], v[88:91]
	v_mfma_f32_16x16x32_bf16 v[80:83], v[162:165], v[212:215], v[80:83]
	v_mfma_f32_16x16x32_bf16 v[72:75], v[172:175], v[212:215], v[72:75]
	v_mfma_f32_16x16x32_bf16 v[128:131], v[166:169], v[184:187], v[128:131]
	v_mfma_f32_16x16x32_bf16 v[120:123], v[176:179], v[184:187], v[120:123]
	v_mfma_f32_16x16x32_bf16 v[112:115], v[166:169], v[200:203], v[112:115]
	v_mfma_f32_16x16x32_bf16 v[104:107], v[176:179], v[200:203], v[104:107]
	v_mfma_f32_16x16x32_bf16 v[96:99], v[166:169], v[208:211], v[96:99]
	v_mfma_f32_16x16x32_bf16 v[88:91], v[176:179], v[208:211], v[88:91]
	v_mfma_f32_16x16x32_bf16 v[80:83], v[166:169], v[216:219], v[80:83]
	v_mfma_f32_16x16x32_bf16 v[72:75], v[176:179], v[216:219], v[72:75]
	s_barrier
	s_setprio 0
	ds_read_b128 v[180:183], v152 offset:16384
	ds_read_b128 v[184:187], v152 offset:17408
	ds_read_b128 v[196:199], v152 offset:18432
	ds_read_b128 v[200:203], v152 offset:19456
	ds_read_b128 v[204:207], v152 offset:20480
	ds_read_b128 v[208:211], v152 offset:21504
	ds_read_b128 v[212:215], v152 offset:22528
	ds_read_b128 v[216:219], v152 offset:23552
	s_add_i32 m0, s69, 0x10000
	s_nop 0
	global_load_lds_dwordx4 v1, s[2:3]
	s_nop 0
	s_add_i32 m0, s69, 0x12000
	s_nop 0
	global_load_lds_dwordx4 v146, s[2:3]
	s_add_u32 s90, s2, 0x40000
	s_addc_u32 s91, s3, 0
	s_add_i32 m0, s69, 0x14000
	s_nop 0
	global_load_lds_dwordx4 v1, s[90:91]
	s_nop 0
	s_add_i32 m0, s69, 0x16000
	s_nop 0
	global_load_lds_dwordx4 v146, s[90:91]
	s_nop 0
	s_add_i32 m0, s69, 0
	s_nop 0
	global_load_lds_dwordx4 v147, s[88:89]
	s_nop 0
	s_add_i32 m0, s69, 0x2000
	s_nop 0
	global_load_lds_dwordx4 v148, s[88:89]
	s_waitcnt vmcnt(8)
	s_waitcnt lgkmcnt(0)
	s_setprio 1
	s_barrier
	v_mfma_f32_16x16x32_bf16 v[60:63], v[138:141], v[180:183], v[60:63]
	v_mfma_f32_16x16x32_bf16 v[52:55], v[154:157], v[180:183], v[52:55]
	v_mfma_f32_16x16x32_bf16 v[44:47], v[138:141], v[196:199], v[44:47]
	v_mfma_f32_16x16x32_bf16 v[36:39], v[154:157], v[196:199], v[36:39]
	v_mfma_f32_16x16x32_bf16 v[28:31], v[138:141], v[204:207], v[28:31]
	v_mfma_f32_16x16x32_bf16 v[20:23], v[154:157], v[204:207], v[20:23]
	v_mfma_f32_16x16x32_bf16 v[12:15], v[138:141], v[212:215], v[12:15]
	v_mfma_f32_16x16x32_bf16 v[4:7], v[154:157], v[212:215], v[4:7]
	v_mfma_f32_16x16x32_bf16 v[60:63], v[142:145], v[184:187], v[60:63]
	v_mfma_f32_16x16x32_bf16 v[52:55], v[158:161], v[184:187], v[52:55]
	v_mfma_f32_16x16x32_bf16 v[44:47], v[142:145], v[200:203], v[44:47]
	v_mfma_f32_16x16x32_bf16 v[36:39], v[158:161], v[200:203], v[36:39]
	v_mfma_f32_16x16x32_bf16 v[28:31], v[142:145], v[208:211], v[28:31]
	v_mfma_f32_16x16x32_bf16 v[20:23], v[158:161], v[208:211], v[20:23]
	v_mfma_f32_16x16x32_bf16 v[12:15], v[142:145], v[216:219], v[12:15]
	v_mfma_f32_16x16x32_bf16 v[4:7], v[158:161], v[216:219], v[4:7]
	v_mfma_f32_16x16x32_bf16 v[68:71], v[162:165], v[180:183], v[68:71]
	v_mfma_f32_16x16x32_bf16 v[56:59], v[172:175], v[180:183], v[56:59]
	v_mfma_f32_16x16x32_bf16 v[48:51], v[162:165], v[196:199], v[48:51]
	v_mfma_f32_16x16x32_bf16 v[40:43], v[172:175], v[196:199], v[40:43]
	v_mfma_f32_16x16x32_bf16 v[32:35], v[162:165], v[204:207], v[32:35]
	v_mfma_f32_16x16x32_bf16 v[24:27], v[172:175], v[204:207], v[24:27]
	v_mfma_f32_16x16x32_bf16 v[16:19], v[162:165], v[212:215], v[16:19]
	v_mfma_f32_16x16x32_bf16 v[8:11], v[172:175], v[212:215], v[8:11]
	v_mfma_f32_16x16x32_bf16 v[68:71], v[166:169], v[184:187], v[68:71]
	v_mfma_f32_16x16x32_bf16 v[56:59], v[176:179], v[184:187], v[56:59]
	v_mfma_f32_16x16x32_bf16 v[48:51], v[166:169], v[200:203], v[48:51]
	v_mfma_f32_16x16x32_bf16 v[40:43], v[176:179], v[200:203], v[40:43]
	v_mfma_f32_16x16x32_bf16 v[32:35], v[166:169], v[208:211], v[32:35]
	v_mfma_f32_16x16x32_bf16 v[24:27], v[176:179], v[208:211], v[24:27]
	v_mfma_f32_16x16x32_bf16 v[16:19], v[166:169], v[216:219], v[16:19]
	v_mfma_f32_16x16x32_bf16 v[8:11], v[176:179], v[216:219], v[8:11]
	s_barrier
	s_setprio 0
	ds_read_b128 v[138:141], v136
	ds_read_b128 v[142:145], v136 offset:1024
	ds_read_b128 v[154:157], v136 offset:2048
	ds_read_b128 v[158:161], v136 offset:3072
	ds_read_b128 v[162:165], v137
	ds_read_b128 v[166:169], v137 offset:1024
	ds_read_b128 v[172:175], v137 offset:2048
	ds_read_b128 v[176:179], v137 offset:3072
	ds_read_b128 v[180:183], v152 offset:32768
	ds_read_b128 v[184:187], v152 offset:33792
	ds_read_b128 v[196:199], v152 offset:34816
	ds_read_b128 v[200:203], v152 offset:35840
	ds_read_b128 v[204:207], v152 offset:36864
	ds_read_b128 v[208:211], v152 offset:37888
	ds_read_b128 v[212:215], v152 offset:38912
	ds_read_b128 v[216:219], v152 offset:39936
	s_add_u32 s88, s88, 0x40000
	s_addc_u32 s89, s89, 0
	s_add_i32 m0, s69, 0x4000
	s_nop 0
	global_load_lds_dwordx4 v147, s[88:89]
	s_nop 0
	s_add_i32 m0, s69, 0x6000
	s_nop 0
	global_load_lds_dwordx4 v148, s[88:89]
	s_waitcnt vmcnt(8)
	s_waitcnt lgkmcnt(0)
	s_setprio 1
	s_barrier
	v_mfma_f32_16x16x32_bf16 v[124:127], v[138:141], v[180:183], v[124:127]
	v_mfma_f32_16x16x32_bf16 v[116:119], v[154:157], v[180:183], v[116:119]
	v_mfma_f32_16x16x32_bf16 v[108:111], v[138:141], v[196:199], v[108:111]
	v_mfma_f32_16x16x32_bf16 v[100:103], v[154:157], v[196:199], v[100:103]
	v_mfma_f32_16x16x32_bf16 v[92:95], v[138:141], v[204:207], v[92:95]
	v_mfma_f32_16x16x32_bf16 v[84:87], v[154:157], v[204:207], v[84:87]
	v_mfma_f32_16x16x32_bf16 v[76:79], v[138:141], v[212:215], v[76:79]
	v_mfma_f32_16x16x32_bf16 v[64:67], v[154:157], v[212:215], v[64:67]
	v_mfma_f32_16x16x32_bf16 v[124:127], v[142:145], v[184:187], v[124:127]
	v_mfma_f32_16x16x32_bf16 v[116:119], v[158:161], v[184:187], v[116:119]
	v_mfma_f32_16x16x32_bf16 v[108:111], v[142:145], v[200:203], v[108:111]
	v_mfma_f32_16x16x32_bf16 v[100:103], v[158:161], v[200:203], v[100:103]
	v_mfma_f32_16x16x32_bf16 v[92:95], v[142:145], v[208:211], v[92:95]
	v_mfma_f32_16x16x32_bf16 v[84:87], v[158:161], v[208:211], v[84:87]
	v_mfma_f32_16x16x32_bf16 v[76:79], v[142:145], v[216:219], v[76:79]
	v_mfma_f32_16x16x32_bf16 v[64:67], v[158:161], v[216:219], v[64:67]
	v_mfma_f32_16x16x32_bf16 v[128:131], v[162:165], v[180:183], v[128:131]
	v_mfma_f32_16x16x32_bf16 v[120:123], v[172:175], v[180:183], v[120:123]
	v_mfma_f32_16x16x32_bf16 v[112:115], v[162:165], v[196:199], v[112:115]
	v_mfma_f32_16x16x32_bf16 v[104:107], v[172:175], v[196:199], v[104:107]
	v_mfma_f32_16x16x32_bf16 v[96:99], v[162:165], v[204:207], v[96:99]
	v_mfma_f32_16x16x32_bf16 v[88:91], v[172:175], v[204:207], v[88:91]
	v_mfma_f32_16x16x32_bf16 v[80:83], v[162:165], v[212:215], v[80:83]
	v_mfma_f32_16x16x32_bf16 v[72:75], v[172:175], v[212:215], v[72:75]
	v_mfma_f32_16x16x32_bf16 v[128:131], v[166:169], v[184:187], v[128:131]
	v_mfma_f32_16x16x32_bf16 v[120:123], v[176:179], v[184:187], v[120:123]
	v_mfma_f32_16x16x32_bf16 v[112:115], v[166:169], v[200:203], v[112:115]
	v_mfma_f32_16x16x32_bf16 v[104:107], v[176:179], v[200:203], v[104:107]
	v_mfma_f32_16x16x32_bf16 v[96:99], v[166:169], v[208:211], v[96:99]
	v_mfma_f32_16x16x32_bf16 v[88:91], v[176:179], v[208:211], v[88:91]
	v_mfma_f32_16x16x32_bf16 v[80:83], v[166:169], v[216:219], v[80:83]
	v_mfma_f32_16x16x32_bf16 v[72:75], v[176:179], v[216:219], v[72:75]
	s_barrier
	s_setprio 0
	ds_read_b128 v[180:183], v152 offset:49152
	ds_read_b128 v[184:187], v152 offset:50176
	ds_read_b128 v[196:199], v152 offset:51200
	ds_read_b128 v[200:203], v152 offset:52224
	ds_read_b128 v[204:207], v152 offset:53248
	ds_read_b128 v[208:211], v152 offset:54272
	ds_read_b128 v[212:215], v152 offset:55296
	ds_read_b128 v[216:219], v152 offset:56320
	s_add_i32 m0, s69, 0x18000
	s_nop 0
	global_load_lds_dwordx4 v1, s[86:87]
	s_nop 0
	s_add_i32 m0, s69, 0x1a000
	s_nop 0
	global_load_lds_dwordx4 v146, s[86:87]
	s_add_u32 s2, s2, 0x40080
	s_addc_u32 s3, s3, 0
	s_add_i32 m0, s69, 0x1c000
	s_nop 0
	global_load_lds_dwordx4 v1, s[2:3]
	s_nop 0
	s_add_i32 m0, s69, 0x1e000
	s_nop 0
	global_load_lds_dwordx4 v146, s[2:3]
	s_nop 0
	s_add_i32 m0, s69, 0x8000
	s_nop 0
	global_load_lds_dwordx4 v147, s[12:13]
	s_nop 0
	s_add_i32 m0, s69, 0xa000
	s_nop 0
	global_load_lds_dwordx4 v148, s[12:13]
	s_waitcnt vmcnt(8)
	s_waitcnt lgkmcnt(0)
	s_setprio 1
	s_barrier
	v_mfma_f32_16x16x32_bf16 v[60:63], v[138:141], v[180:183], v[60:63]
	v_mfma_f32_16x16x32_bf16 v[52:55], v[154:157], v[180:183], v[52:55]
	v_mfma_f32_16x16x32_bf16 v[44:47], v[138:141], v[196:199], v[44:47]
	v_mfma_f32_16x16x32_bf16 v[36:39], v[154:157], v[196:199], v[36:39]
	v_mfma_f32_16x16x32_bf16 v[28:31], v[138:141], v[204:207], v[28:31]
	v_mfma_f32_16x16x32_bf16 v[20:23], v[154:157], v[204:207], v[20:23]
	v_mfma_f32_16x16x32_bf16 v[12:15], v[138:141], v[212:215], v[12:15]
	v_mfma_f32_16x16x32_bf16 v[4:7], v[154:157], v[212:215], v[4:7]
	v_mfma_f32_16x16x32_bf16 v[60:63], v[142:145], v[184:187], v[60:63]
	v_mfma_f32_16x16x32_bf16 v[52:55], v[158:161], v[184:187], v[52:55]
	v_mfma_f32_16x16x32_bf16 v[44:47], v[142:145], v[200:203], v[44:47]
	v_mfma_f32_16x16x32_bf16 v[36:39], v[158:161], v[200:203], v[36:39]
	v_mfma_f32_16x16x32_bf16 v[28:31], v[142:145], v[208:211], v[28:31]
	v_mfma_f32_16x16x32_bf16 v[20:23], v[158:161], v[208:211], v[20:23]
	v_mfma_f32_16x16x32_bf16 v[12:15], v[142:145], v[216:219], v[12:15]
	v_mfma_f32_16x16x32_bf16 v[4:7], v[158:161], v[216:219], v[4:7]
	v_mfma_f32_16x16x32_bf16 v[68:71], v[162:165], v[180:183], v[68:71]
	v_mfma_f32_16x16x32_bf16 v[56:59], v[172:175], v[180:183], v[56:59]
	v_mfma_f32_16x16x32_bf16 v[48:51], v[162:165], v[196:199], v[48:51]
	v_mfma_f32_16x16x32_bf16 v[40:43], v[172:175], v[196:199], v[40:43]
	v_mfma_f32_16x16x32_bf16 v[32:35], v[162:165], v[204:207], v[32:35]
	v_mfma_f32_16x16x32_bf16 v[24:27], v[172:175], v[204:207], v[24:27]
	v_mfma_f32_16x16x32_bf16 v[16:19], v[162:165], v[212:215], v[16:19]
	v_mfma_f32_16x16x32_bf16 v[8:11], v[172:175], v[212:215], v[8:11]
	v_mfma_f32_16x16x32_bf16 v[68:71], v[166:169], v[184:187], v[68:71]
	v_mfma_f32_16x16x32_bf16 v[56:59], v[176:179], v[184:187], v[56:59]
	v_mfma_f32_16x16x32_bf16 v[48:51], v[166:169], v[200:203], v[48:51]
	v_mfma_f32_16x16x32_bf16 v[40:43], v[176:179], v[200:203], v[40:43]
	v_mfma_f32_16x16x32_bf16 v[32:35], v[166:169], v[208:211], v[32:35]
	v_mfma_f32_16x16x32_bf16 v[24:27], v[176:179], v[208:211], v[24:27]
	v_mfma_f32_16x16x32_bf16 v[16:19], v[166:169], v[216:219], v[16:19]
	v_mfma_f32_16x16x32_bf16 v[8:11], v[176:179], v[216:219], v[8:11]
	s_barrier
	s_setprio 0
	s_add_i32 s2, s29, 2
	s_cmp_gt_u32 s29, 13
	s_cbranch_scc1 .LBB0_1196
	s_mov_b32 s29, s2
	s_branch .LBB0_1072
